# v33: EpiRes early second-half residual loads ordered after each first-half pair; first-half vmcnt(0) replaced by counted waits 14/12/10/8; second half single vmcnt(8)
# speedup vs baseline: 1.0068x; 1.0068x over previous
.LBB0_265:
	s_mov_b32 s98, 0x40000
	s_mov_b32 s99, 0
	v_and_b32_e32 v121, 64, v230
	v_xor_b32_e32 v120, 16, v230
	v_add_u32_e32 v121, 64, v121
	v_cmp_lt_i32_e32 vcc, v120, v121
	s_lshl_b32 s42, s75, 8
	s_lshl_b32 s34, s15, 8
	v_cndmask_b32_e32 v120, v230, v120, vcc
	v_add_u32_e32 v156, s42, v225
	s_ashr_i32 s35, s34, 31
	v_lshlrev_b32_e32 v167, 2, v120
	v_xor_b32_e32 v120, 32, v230
	v_cmp_lt_i32_e32 vcc, v120, v121
	s_lshl_b64 s[34:35], s[34:35], 1
	v_ashrrev_i32_e32 v157, 31, v156
	v_cndmask_b32_e32 v120, v230, v120, vcc
	v_lshl_add_u64 v[158:159], v[204:205], 0, s[34:35]
	v_lshlrev_b64 v[172:173], 11, v[156:157]
	v_lshlrev_b32_e32 v166, 2, v120
	v_lshl_add_u64 v[120:121], v[158:159], 0, v[172:173]
	v_lshl_add_u64 v[190:191], v[120:121], 0, s[98:99]
	global_load_dwordx4 v[168:171], v[120:121], off
	global_load_dwordx4 v[152:155], v[120:121], off offset:256
	global_load_dwordx4 v[182:185], v[190:191], off
	global_load_dwordx4 v[186:189], v[190:191], off offset:256
	v_or_b32_e32 v120, 16, v156
	v_ashrrev_i32_e32 v121, 31, v120
	v_lshlrev_b64 v[164:165], 11, v[120:121]
	v_lshl_add_u64 v[120:121], v[158:159], 0, v[164:165]
	v_lshl_add_u64 v[190:191], v[120:121], 0, s[98:99]
	global_load_dwordx4 v[148:151], v[120:121], off
	global_load_dwordx4 v[144:147], v[120:121], off offset:256
	global_load_dwordx4 v[216:219], v[190:191], off
	global_load_dwordx4 v[220:223], v[190:191], off offset:256
	v_or_b32_e32 v120, 32, v156
	v_ashrrev_i32_e32 v121, 31, v120
	v_lshlrev_b64 v[162:163], 11, v[120:121]
	v_lshl_add_u64 v[120:121], v[158:159], 0, v[162:163]
	v_lshl_add_u64 v[190:191], v[120:121], 0, s[98:99]
	global_load_dwordx4 v[140:143], v[120:121], off
	global_load_dwordx4 v[136:139], v[120:121], off offset:256
	global_load_dwordx4 v[236:239], v[190:191], off
	global_load_dwordx4 v[240:243], v[190:191], off offset:256
	v_or_b32_e32 v120, 48, v156
	v_ashrrev_i32_e32 v121, 31, v120
	v_lshlrev_b64 v[160:161], 11, v[120:121]
	v_lshl_add_u64 v[120:121], v[158:159], 0, v[160:161]
	v_lshl_add_u64 v[190:191], v[120:121], 0, s[98:99]
	global_load_dwordx4 v[132:135], v[120:121], off
	s_nop 0
	global_load_dwordx4 v[120:123], v[120:121], off offset:256
	global_load_dwordx4 v[246:249], v[190:191], off
	global_load_dwordx4 v[250:253], v[190:191], off offset:256
	s_mov_b32 s15, s1
	s_ashr_i32 s43, s42, 31
	s_waitcnt vmcnt(14)
	v_lshlrev_b32_e32 v174, 16, v168
	v_and_b32_e32 v175, 0xffff0000, v168
	v_lshlrev_b32_e32 v168, 16, v169
	v_and_b32_e32 v169, 0xffff0000, v169
	v_pk_fma_f32 v[130:131], v[130:131], 0.5, v[168:169] op_sel_hi:[1,0,1]
	v_pk_fma_f32 v[168:169], v[128:129], 0.5, v[174:175] op_sel_hi:[1,0,1]
	v_cvt_pk_bf16_f32 v129, v130, v131
	v_mul_f32_e32 v157, v169, v169
	v_mul_f32_e32 v131, v131, v131
	v_fmac_f32_e32 v157, v168, v168
	v_fmac_f32_e32 v131, v130, v130
	v_add_f32_e32 v157, v157, v131
	v_lshlrev_b32_e32 v130, 16, v170
	v_and_b32_e32 v131, 0xffff0000, v170
	v_cvt_pk_bf16_f32 v128, v168, v169
	v_lshlrev_b32_e32 v168, 16, v171
	v_and_b32_e32 v169, 0xffff0000, v171
	v_pk_fma_f32 v[124:125], v[124:125], 0.5, v[130:131] op_sel_hi:[1,0,1]
	v_pk_fma_f32 v[126:127], v[126:127], 0.5, v[168:169] op_sel_hi:[1,0,1]
	v_cvt_pk_bf16_f32 v130, v124, v125
	v_mul_f32_e32 v125, v125, v125
	v_fmac_f32_e32 v125, v124, v124
	v_mul_f32_e32 v124, v127, v127
	v_fmac_f32_e32 v124, v126, v126
	v_add_f32_e32 v124, v125, v124
	v_add_f32_e32 v157, v157, v124
	v_lshl_add_u64 v[124:125], s[78:79], 0, v[172:173]
	v_lshl_add_u64 v[124:125], v[124:125], 0, s[34:35]
	v_lshl_add_u64 v[124:125], v[124:125], 0, s[14:15]
	v_cvt_pk_bf16_f32 v131, v126, v127
	v_lshl_add_u64 v[124:125], v[124:125], 0, v[200:201]
	global_store_dwordx4 v[124:125], v[128:131], off
	v_lshlrev_b32_e32 v126, 16, v152
	v_and_b32_e32 v127, 0xffff0000, v152
	v_lshlrev_b32_e32 v128, 16, v153
	v_and_b32_e32 v129, 0xffff0000, v153
	v_pk_fma_f32 v[118:119], v[118:119], 0.5, v[128:129] op_sel_hi:[1,0,1]
	v_pk_fma_f32 v[126:127], v[116:117], 0.5, v[126:127] op_sel_hi:[1,0,1]
	v_cvt_pk_bf16_f32 v117, v118, v119
	v_cvt_pk_bf16_f32 v116, v126, v127
	v_mul_f32_e32 v127, v127, v127
	v_mul_f32_e32 v119, v119, v119
	v_fmac_f32_e32 v127, v126, v126
	v_fmac_f32_e32 v119, v118, v118
	v_add_f32_e32 v118, v127, v119
	v_add_f32_e32 v128, v157, v118
	v_lshlrev_b32_e32 v118, 16, v154
	v_and_b32_e32 v119, 0xffff0000, v154
	v_lshlrev_b32_e32 v126, 16, v155
	v_and_b32_e32 v127, 0xffff0000, v155
	v_pk_fma_f32 v[112:113], v[112:113], 0.5, v[118:119] op_sel_hi:[1,0,1]
	v_pk_fma_f32 v[114:115], v[114:115], 0.5, v[126:127] op_sel_hi:[1,0,1]
	v_cvt_pk_bf16_f32 v118, v112, v113
	v_mul_f32_e32 v113, v113, v113
	v_cvt_pk_bf16_f32 v119, v114, v115
	v_fmac_f32_e32 v113, v112, v112
	v_mul_f32_e32 v112, v115, v115
	v_fmac_f32_e32 v112, v114, v114
	global_store_dwordx4 v[124:125], v[116:119], off offset:256
	s_waitcnt vmcnt(12)
	v_lshlrev_b32_e32 v114, 16, v148
	v_and_b32_e32 v115, 0xffff0000, v148
	v_lshlrev_b32_e32 v116, 16, v149
	v_and_b32_e32 v117, 0xffff0000, v149
	v_pk_fma_f32 v[110:111], v[110:111], 0.5, v[116:117] op_sel_hi:[1,0,1]
	v_pk_fma_f32 v[114:115], v[108:109], 0.5, v[114:115] op_sel_hi:[1,0,1]
	v_cvt_pk_bf16_f32 v109, v110, v111
	v_cvt_pk_bf16_f32 v108, v114, v115
	v_mul_f32_e32 v115, v115, v115
	v_mul_f32_e32 v111, v111, v111
	v_fmac_f32_e32 v115, v114, v114
	v_fmac_f32_e32 v111, v110, v110
	v_add_f32_e32 v116, v115, v111
	v_lshlrev_b32_e32 v110, 16, v150
	v_and_b32_e32 v111, 0xffff0000, v150
	v_lshlrev_b32_e32 v114, 16, v151
	v_and_b32_e32 v115, 0xffff0000, v151
	v_pk_fma_f32 v[104:105], v[104:105], 0.5, v[110:111] op_sel_hi:[1,0,1]
	v_pk_fma_f32 v[106:107], v[106:107], 0.5, v[114:115] op_sel_hi:[1,0,1]
	v_cvt_pk_bf16_f32 v110, v104, v105
	v_mul_f32_e32 v105, v105, v105
	v_fmac_f32_e32 v105, v104, v104
	v_mul_f32_e32 v104, v107, v107
	v_fmac_f32_e32 v104, v106, v106
	v_add_f32_e32 v104, v105, v104
	v_add_f32_e32 v114, v116, v104
	v_lshl_add_u64 v[104:105], s[78:79], 0, v[164:165]
	v_lshl_add_u64 v[104:105], v[104:105], 0, s[34:35]
	v_lshl_add_u64 v[104:105], v[104:105], 0, s[14:15]
	v_cvt_pk_bf16_f32 v111, v106, v107
	v_lshl_add_u64 v[104:105], v[104:105], 0, v[200:201]
	global_store_dwordx4 v[104:105], v[108:111], off
	v_lshlrev_b32_e32 v106, 16, v144
	v_and_b32_e32 v107, 0xffff0000, v144
	v_lshlrev_b32_e32 v108, 16, v145
	v_and_b32_e32 v109, 0xffff0000, v145
	v_pk_fma_f32 v[102:103], v[102:103], 0.5, v[108:109] op_sel_hi:[1,0,1]
	v_pk_fma_f32 v[106:107], v[100:101], 0.5, v[106:107] op_sel_hi:[1,0,1]
	v_cvt_pk_bf16_f32 v101, v102, v103
	v_cvt_pk_bf16_f32 v100, v106, v107
	v_mul_f32_e32 v107, v107, v107
	v_mul_f32_e32 v103, v103, v103
	v_fmac_f32_e32 v107, v106, v106
	v_fmac_f32_e32 v103, v102, v102
	v_add_f32_e32 v102, v107, v103
	v_add_f32_e32 v108, v114, v102
	v_lshlrev_b32_e32 v102, 16, v146
	v_and_b32_e32 v103, 0xffff0000, v146
	v_lshlrev_b32_e32 v106, 16, v147
	v_and_b32_e32 v107, 0xffff0000, v147
	v_pk_fma_f32 v[96:97], v[96:97], 0.5, v[102:103] op_sel_hi:[1,0,1]
	v_pk_fma_f32 v[98:99], v[98:99], 0.5, v[106:107] op_sel_hi:[1,0,1]
	v_cvt_pk_bf16_f32 v102, v96, v97
	v_mul_f32_e32 v97, v97, v97
	v_cvt_pk_bf16_f32 v103, v98, v99
	v_fmac_f32_e32 v97, v96, v96
	v_mul_f32_e32 v96, v99, v99
	v_fmac_f32_e32 v96, v98, v98
	global_store_dwordx4 v[104:105], v[100:103], off offset:256
	s_waitcnt vmcnt(10)
	v_lshlrev_b32_e32 v98, 16, v140
	v_and_b32_e32 v99, 0xffff0000, v140
	v_lshlrev_b32_e32 v100, 16, v141
	v_and_b32_e32 v101, 0xffff0000, v141
	v_pk_fma_f32 v[94:95], v[94:95], 0.5, v[100:101] op_sel_hi:[1,0,1]
	v_pk_fma_f32 v[98:99], v[92:93], 0.5, v[98:99] op_sel_hi:[1,0,1]
	v_cvt_pk_bf16_f32 v93, v94, v95
	v_cvt_pk_bf16_f32 v92, v98, v99
	v_mul_f32_e32 v99, v99, v99
	v_mul_f32_e32 v95, v95, v95
	v_fmac_f32_e32 v99, v98, v98
	v_fmac_f32_e32 v95, v94, v94
	v_add_f32_e32 v100, v99, v95
	v_lshlrev_b32_e32 v94, 16, v142
	v_and_b32_e32 v95, 0xffff0000, v142
	v_lshlrev_b32_e32 v98, 16, v143
	v_and_b32_e32 v99, 0xffff0000, v143
	v_pk_fma_f32 v[88:89], v[88:89], 0.5, v[94:95] op_sel_hi:[1,0,1]
	v_pk_fma_f32 v[90:91], v[90:91], 0.5, v[98:99] op_sel_hi:[1,0,1]
	v_cvt_pk_bf16_f32 v94, v88, v89
	v_mul_f32_e32 v89, v89, v89
	v_fmac_f32_e32 v89, v88, v88
	v_mul_f32_e32 v88, v91, v91
	v_fmac_f32_e32 v88, v90, v90
	v_add_f32_e32 v88, v89, v88
	v_add_f32_e32 v98, v100, v88
	v_lshl_add_u64 v[88:89], s[78:79], 0, v[162:163]
	v_lshl_add_u64 v[88:89], v[88:89], 0, s[34:35]
	v_lshl_add_u64 v[88:89], v[88:89], 0, s[14:15]
	v_cvt_pk_bf16_f32 v95, v90, v91
	v_lshl_add_u64 v[88:89], v[88:89], 0, v[200:201]
	global_store_dwordx4 v[88:89], v[92:95], off
	v_lshlrev_b32_e32 v90, 16, v136
	v_and_b32_e32 v91, 0xffff0000, v136
	v_lshlrev_b32_e32 v92, 16, v137
	v_and_b32_e32 v93, 0xffff0000, v137
	v_pk_fma_f32 v[86:87], v[86:87], 0.5, v[92:93] op_sel_hi:[1,0,1]
	v_pk_fma_f32 v[90:91], v[84:85], 0.5, v[90:91] op_sel_hi:[1,0,1]
	v_cvt_pk_bf16_f32 v85, v86, v87
	v_cvt_pk_bf16_f32 v84, v90, v91
	v_mul_f32_e32 v91, v91, v91
	v_mul_f32_e32 v87, v87, v87
	v_fmac_f32_e32 v91, v90, v90
	v_fmac_f32_e32 v87, v86, v86
	v_add_f32_e32 v86, v91, v87
	v_add_f32_e32 v92, v98, v86
	v_lshlrev_b32_e32 v86, 16, v138
	v_and_b32_e32 v87, 0xffff0000, v138
	v_lshlrev_b32_e32 v90, 16, v139
	v_and_b32_e32 v91, 0xffff0000, v139
	v_pk_fma_f32 v[80:81], v[80:81], 0.5, v[86:87] op_sel_hi:[1,0,1]
	v_pk_fma_f32 v[82:83], v[82:83], 0.5, v[90:91] op_sel_hi:[1,0,1]
	v_cvt_pk_bf16_f32 v86, v80, v81
	v_mul_f32_e32 v81, v81, v81
	v_cvt_pk_bf16_f32 v87, v82, v83
	v_fmac_f32_e32 v81, v80, v80
	v_mul_f32_e32 v80, v83, v83
	v_fmac_f32_e32 v80, v82, v82
	global_store_dwordx4 v[88:89], v[84:87], off offset:256
	s_waitcnt vmcnt(8)
	v_lshlrev_b32_e32 v82, 16, v132
	v_and_b32_e32 v83, 0xffff0000, v132
	v_lshlrev_b32_e32 v84, 16, v133
	v_and_b32_e32 v85, 0xffff0000, v133
	v_pk_fma_f32 v[78:79], v[78:79], 0.5, v[84:85] op_sel_hi:[1,0,1]
	v_pk_fma_f32 v[82:83], v[76:77], 0.5, v[82:83] op_sel_hi:[1,0,1]
	v_cvt_pk_bf16_f32 v77, v78, v79
	v_cvt_pk_bf16_f32 v76, v82, v83
	v_mul_f32_e32 v83, v83, v83
	v_mul_f32_e32 v79, v79, v79
	v_fmac_f32_e32 v83, v82, v82
	v_fmac_f32_e32 v79, v78, v78
	v_add_f32_e32 v84, v83, v79
	v_lshlrev_b32_e32 v78, 16, v134
	v_and_b32_e32 v79, 0xffff0000, v134
	v_lshlrev_b32_e32 v82, 16, v135
	v_and_b32_e32 v83, 0xffff0000, v135
	v_pk_fma_f32 v[72:73], v[72:73], 0.5, v[78:79] op_sel_hi:[1,0,1]
	v_pk_fma_f32 v[74:75], v[74:75], 0.5, v[82:83] op_sel_hi:[1,0,1]
	v_cvt_pk_bf16_f32 v78, v72, v73
	v_mul_f32_e32 v73, v73, v73
	v_fmac_f32_e32 v73, v72, v72
	v_mul_f32_e32 v72, v75, v75
	v_fmac_f32_e32 v72, v74, v74
	v_add_f32_e32 v72, v73, v72
	v_add_f32_e32 v82, v84, v72
	v_lshl_add_u64 v[72:73], s[78:79], 0, v[160:161]
	v_lshl_add_u64 v[72:73], v[72:73], 0, s[34:35]
	v_lshl_add_u64 v[72:73], v[72:73], 0, s[14:15]
	v_cvt_pk_bf16_f32 v79, v74, v75
	v_lshl_add_u64 v[72:73], v[72:73], 0, v[200:201]
	global_store_dwordx4 v[72:73], v[76:79], off
	v_lshlrev_b32_e32 v74, 16, v120
	v_and_b32_e32 v75, 0xffff0000, v120
	v_lshlrev_b32_e32 v76, 16, v121
	v_and_b32_e32 v77, 0xffff0000, v121
	v_pk_fma_f32 v[70:71], v[70:71], 0.5, v[76:77] op_sel_hi:[1,0,1]
	v_pk_fma_f32 v[74:75], v[68:69], 0.5, v[74:75] op_sel_hi:[1,0,1]
	v_cvt_pk_bf16_f32 v69, v70, v71
	v_cvt_pk_bf16_f32 v68, v74, v75
	v_mul_f32_e32 v75, v75, v75
	v_mul_f32_e32 v71, v71, v71
	v_fmac_f32_e32 v75, v74, v74
	v_fmac_f32_e32 v71, v70, v70
	v_add_f32_e32 v70, v75, v71
	v_add_f32_e32 v76, v82, v70
	v_lshlrev_b32_e32 v70, 16, v122
	v_and_b32_e32 v71, 0xffff0000, v122
	v_lshlrev_b32_e32 v74, 16, v123
	v_and_b32_e32 v75, 0xffff0000, v123
	v_pk_fma_f32 v[64:65], v[64:65], 0.5, v[70:71] op_sel_hi:[1,0,1]
	v_pk_fma_f32 v[66:67], v[66:67], 0.5, v[74:75] op_sel_hi:[1,0,1]
	v_cvt_pk_bf16_f32 v70, v64, v65
	v_mul_f32_e32 v65, v65, v65
	v_fmac_f32_e32 v65, v64, v64
	v_mul_f32_e32 v64, v67, v67
	v_fmac_f32_e32 v64, v66, v66
	v_add_f32_e32 v112, v113, v112
	v_add_f32_e32 v96, v97, v96
	v_add_f32_e32 v80, v81, v80
	v_add_f32_e32 v64, v65, v64
	v_add_f32_e32 v112, v112, v128
	v_add_f32_e32 v96, v96, v108
	v_add_f32_e32 v80, v80, v92
	v_add_f32_e32 v64, v64, v76
	ds_bpermute_b32 v113, v167, v112
	ds_bpermute_b32 v97, v167, v96
	ds_bpermute_b32 v81, v167, v80
	ds_bpermute_b32 v65, v167, v64
	v_cvt_pk_bf16_f32 v71, v66, v67
	s_waitcnt lgkmcnt(3)
	v_add_f32_e32 v112, v112, v113
	s_waitcnt lgkmcnt(2)
	v_add_f32_e32 v96, v96, v97
	s_waitcnt lgkmcnt(1)
	v_add_f32_e32 v80, v80, v81
	s_waitcnt lgkmcnt(0)
	v_add_f32_e32 v64, v64, v65
	ds_bpermute_b32 v113, v166, v112
	ds_bpermute_b32 v97, v166, v96
	ds_bpermute_b32 v81, v166, v80
	ds_bpermute_b32 v65, v166, v64
	v_lshl_add_u64 v[92:93], s[42:43], 2, v[206:207]
	global_store_dwordx4 v[72:73], v[68:71], off offset:256
	s_and_saveexec_b64 s[42:43], s[2:3]
	v_readlane_b32 s92, v245, 60
	v_readlane_b32 s93, v245, 61
	v_readlane_b32 s94, v245, 62
	v_readlane_b32 s95, v245, 63
	v_readlane_b32 s97, v244, 0
	s_cbranch_execz .LBB0_267
	s_waitcnt lgkmcnt(3)
	v_add_f32_e32 v67, v112, v113
	s_waitcnt lgkmcnt(0)
	v_add_f32_e32 v64, v64, v65
	v_add_f32_e32 v65, v80, v81
	v_add_f32_e32 v66, v96, v97
	global_atomic_add_f32 v[92:93], v67, off
	global_atomic_add_f32 v[92:93], v66, off offset:64
	global_atomic_add_f32 v[92:93], v65, off offset:128
	global_atomic_add_f32 v[92:93], v64, off offset:192
.LBB0_267:
	s_or_b64 exec, exec, s[42:43]
	s_waitcnt vmcnt(8)
	v_add_u32_e32 v64, 0x80, v156
	s_waitcnt lgkmcnt(0)
	v_ashrrev_i32_e32 v65, 31, v64
	v_lshlrev_b64 v[104:105], 11, v[64:65]
	v_lshl_add_u64 v[64:65], v[158:159], 0, v[104:105]
	v_mov_b32_e32 v100, v182
	v_mov_b32_e32 v101, v183
	v_mov_b32_e32 v102, v184
	v_mov_b32_e32 v103, v185
	v_mov_b32_e32 v88, v186
	v_mov_b32_e32 v89, v187
	v_mov_b32_e32 v90, v188
	v_mov_b32_e32 v91, v189
	v_add_u32_e32 v64, 0x90, v156
	v_ashrrev_i32_e32 v65, 31, v64
	v_lshlrev_b64 v[98:99], 11, v[64:65]
	v_lshl_add_u64 v[64:65], v[158:159], 0, v[98:99]
	v_mov_b32_e32 v84, v216
	v_mov_b32_e32 v85, v217
	v_mov_b32_e32 v86, v218
	v_mov_b32_e32 v87, v219
	v_mov_b32_e32 v80, v220
	v_mov_b32_e32 v81, v221
	v_mov_b32_e32 v82, v222
	v_mov_b32_e32 v83, v223
	v_add_u32_e32 v64, 0xa0, v156
	v_ashrrev_i32_e32 v65, 31, v64
	v_lshlrev_b64 v[96:97], 11, v[64:65]
	v_lshl_add_u64 v[64:65], v[158:159], 0, v[96:97]
	v_mov_b32_e32 v76, v236
	v_mov_b32_e32 v77, v237
	v_mov_b32_e32 v78, v238
	v_mov_b32_e32 v79, v239
	v_mov_b32_e32 v72, v240
	v_mov_b32_e32 v73, v241
	v_mov_b32_e32 v74, v242
	v_mov_b32_e32 v75, v243
	v_add_u32_e32 v64, 0xb0, v156
	v_ashrrev_i32_e32 v65, 31, v64
	v_lshlrev_b64 v[94:95], 11, v[64:65]
	v_lshl_add_u64 v[64:65], v[158:159], 0, v[94:95]
	v_mov_b32_e32 v68, v246
	v_mov_b32_e32 v69, v247
	v_mov_b32_e32 v70, v248
	v_mov_b32_e32 v71, v249
	s_nop 0
	v_mov_b32_e32 v64, v250
	v_mov_b32_e32 v65, v251
	v_mov_b32_e32 v66, v252
	v_mov_b32_e32 v67, v253
	v_lshlrev_b32_e32 v106, 16, v100
	v_and_b32_e32 v107, 0xffff0000, v100
	v_lshlrev_b32_e32 v100, 16, v101
	v_and_b32_e32 v101, 0xffff0000, v101
	v_pk_fma_f32 v[62:63], v[62:63], 0.5, v[100:101] op_sel_hi:[1,0,1]
	v_pk_fma_f32 v[100:101], v[60:61], 0.5, v[106:107] op_sel_hi:[1,0,1]
	v_cvt_pk_bf16_f32 v61, v62, v63
	v_cvt_pk_bf16_f32 v60, v100, v101
	v_mul_f32_e32 v101, v101, v101
	v_mul_f32_e32 v63, v63, v63
	v_fmac_f32_e32 v101, v100, v100
	v_fmac_f32_e32 v63, v62, v62
	v_add_f32_e32 v106, v101, v63
	v_lshlrev_b32_e32 v62, 16, v102
	v_and_b32_e32 v63, 0xffff0000, v102
	v_lshlrev_b32_e32 v100, 16, v103
	v_and_b32_e32 v101, 0xffff0000, v103
	v_pk_fma_f32 v[56:57], v[56:57], 0.5, v[62:63] op_sel_hi:[1,0,1]
	v_pk_fma_f32 v[58:59], v[58:59], 0.5, v[100:101] op_sel_hi:[1,0,1]
	v_cvt_pk_bf16_f32 v62, v56, v57
	v_mul_f32_e32 v57, v57, v57
	v_fmac_f32_e32 v57, v56, v56
	v_mul_f32_e32 v56, v59, v59
	v_fmac_f32_e32 v56, v58, v58
	v_add_f32_e32 v56, v57, v56
	v_add_f32_e32 v100, v106, v56
	v_lshl_add_u64 v[56:57], s[78:79], 0, v[104:105]
	v_lshl_add_u64 v[56:57], v[56:57], 0, s[34:35]
	v_lshl_add_u64 v[56:57], v[56:57], 0, s[14:15]
	v_cvt_pk_bf16_f32 v63, v58, v59
	v_lshl_add_u64 v[56:57], v[56:57], 0, v[200:201]
	global_store_dwordx4 v[56:57], v[60:63], off
	v_lshlrev_b32_e32 v58, 16, v88
	v_and_b32_e32 v59, 0xffff0000, v88
	v_lshlrev_b32_e32 v60, 16, v89
	v_and_b32_e32 v61, 0xffff0000, v89
	v_pk_fma_f32 v[54:55], v[54:55], 0.5, v[60:61] op_sel_hi:[1,0,1]
	v_pk_fma_f32 v[58:59], v[52:53], 0.5, v[58:59] op_sel_hi:[1,0,1]
	v_cvt_pk_bf16_f32 v53, v54, v55
	v_cvt_pk_bf16_f32 v52, v58, v59
	v_mul_f32_e32 v59, v59, v59
	v_mul_f32_e32 v55, v55, v55
	v_fmac_f32_e32 v59, v58, v58
	v_fmac_f32_e32 v55, v54, v54
	v_add_f32_e32 v54, v59, v55
	v_add_f32_e32 v60, v100, v54
	v_lshlrev_b32_e32 v54, 16, v90
	v_and_b32_e32 v55, 0xffff0000, v90
	v_lshlrev_b32_e32 v58, 16, v91
	v_and_b32_e32 v59, 0xffff0000, v91
	v_pk_fma_f32 v[48:49], v[48:49], 0.5, v[54:55] op_sel_hi:[1,0,1]
	v_pk_fma_f32 v[50:51], v[50:51], 0.5, v[58:59] op_sel_hi:[1,0,1]
	v_cvt_pk_bf16_f32 v54, v48, v49
	v_mul_f32_e32 v49, v49, v49
	v_cvt_pk_bf16_f32 v55, v50, v51
	v_fmac_f32_e32 v49, v48, v48
	v_mul_f32_e32 v48, v51, v51
	v_fmac_f32_e32 v48, v50, v50
	global_store_dwordx4 v[56:57], v[52:55], off offset:256
	v_lshlrev_b32_e32 v50, 16, v84
	v_and_b32_e32 v51, 0xffff0000, v84
	v_lshlrev_b32_e32 v52, 16, v85
	v_and_b32_e32 v53, 0xffff0000, v85
	v_pk_fma_f32 v[46:47], v[46:47], 0.5, v[52:53] op_sel_hi:[1,0,1]
	v_pk_fma_f32 v[50:51], v[44:45], 0.5, v[50:51] op_sel_hi:[1,0,1]
	v_cvt_pk_bf16_f32 v45, v46, v47
	v_cvt_pk_bf16_f32 v44, v50, v51
	v_mul_f32_e32 v51, v51, v51
	v_mul_f32_e32 v47, v47, v47
	v_fmac_f32_e32 v51, v50, v50
	v_fmac_f32_e32 v47, v46, v46
	v_add_f32_e32 v52, v51, v47
	v_lshlrev_b32_e32 v46, 16, v86
	v_and_b32_e32 v47, 0xffff0000, v86
	v_lshlrev_b32_e32 v50, 16, v87
	v_and_b32_e32 v51, 0xffff0000, v87
	v_pk_fma_f32 v[40:41], v[40:41], 0.5, v[46:47] op_sel_hi:[1,0,1]
	v_pk_fma_f32 v[42:43], v[42:43], 0.5, v[50:51] op_sel_hi:[1,0,1]
	v_cvt_pk_bf16_f32 v46, v40, v41
	v_mul_f32_e32 v41, v41, v41
	v_fmac_f32_e32 v41, v40, v40
	v_mul_f32_e32 v40, v43, v43
	v_fmac_f32_e32 v40, v42, v42
	v_add_f32_e32 v40, v41, v40
	v_add_f32_e32 v50, v52, v40
	v_lshl_add_u64 v[40:41], s[78:79], 0, v[98:99]
	v_lshl_add_u64 v[40:41], v[40:41], 0, s[34:35]
	v_lshl_add_u64 v[40:41], v[40:41], 0, s[14:15]
	v_cvt_pk_bf16_f32 v47, v42, v43
	v_lshl_add_u64 v[40:41], v[40:41], 0, v[200:201]
	global_store_dwordx4 v[40:41], v[44:47], off
	v_lshlrev_b32_e32 v42, 16, v80
	v_and_b32_e32 v43, 0xffff0000, v80
	v_lshlrev_b32_e32 v44, 16, v81
	v_and_b32_e32 v45, 0xffff0000, v81
	v_pk_fma_f32 v[38:39], v[38:39], 0.5, v[44:45] op_sel_hi:[1,0,1]
	v_pk_fma_f32 v[42:43], v[36:37], 0.5, v[42:43] op_sel_hi:[1,0,1]
	v_cvt_pk_bf16_f32 v37, v38, v39
	v_cvt_pk_bf16_f32 v36, v42, v43
	v_mul_f32_e32 v43, v43, v43
	v_mul_f32_e32 v39, v39, v39
	v_fmac_f32_e32 v43, v42, v42
	v_fmac_f32_e32 v39, v38, v38
	v_add_f32_e32 v38, v43, v39
	v_add_f32_e32 v44, v50, v38
	v_lshlrev_b32_e32 v38, 16, v82
	v_and_b32_e32 v39, 0xffff0000, v82
	v_lshlrev_b32_e32 v42, 16, v83
	v_and_b32_e32 v43, 0xffff0000, v83
	v_pk_fma_f32 v[32:33], v[32:33], 0.5, v[38:39] op_sel_hi:[1,0,1]
	v_pk_fma_f32 v[34:35], v[34:35], 0.5, v[42:43] op_sel_hi:[1,0,1]
	v_cvt_pk_bf16_f32 v38, v32, v33
	v_mul_f32_e32 v33, v33, v33
	v_cvt_pk_bf16_f32 v39, v34, v35
	v_fmac_f32_e32 v33, v32, v32
	v_mul_f32_e32 v32, v35, v35
	v_fmac_f32_e32 v32, v34, v34
	global_store_dwordx4 v[40:41], v[36:39], off offset:256
	v_lshlrev_b32_e32 v34, 16, v76
	v_and_b32_e32 v35, 0xffff0000, v76
	v_lshlrev_b32_e32 v36, 16, v77
	v_and_b32_e32 v37, 0xffff0000, v77
	v_pk_fma_f32 v[30:31], v[30:31], 0.5, v[36:37] op_sel_hi:[1,0,1]
	v_pk_fma_f32 v[34:35], v[28:29], 0.5, v[34:35] op_sel_hi:[1,0,1]
	v_cvt_pk_bf16_f32 v29, v30, v31
	v_cvt_pk_bf16_f32 v28, v34, v35
	v_mul_f32_e32 v35, v35, v35
	v_mul_f32_e32 v31, v31, v31
	v_fmac_f32_e32 v35, v34, v34
	v_fmac_f32_e32 v31, v30, v30
	v_add_f32_e32 v36, v35, v31
	v_lshlrev_b32_e32 v30, 16, v78
	v_and_b32_e32 v31, 0xffff0000, v78
	v_lshlrev_b32_e32 v34, 16, v79
	v_and_b32_e32 v35, 0xffff0000, v79
	v_pk_fma_f32 v[24:25], v[24:25], 0.5, v[30:31] op_sel_hi:[1,0,1]
	v_pk_fma_f32 v[26:27], v[26:27], 0.5, v[34:35] op_sel_hi:[1,0,1]
	v_cvt_pk_bf16_f32 v30, v24, v25
	v_mul_f32_e32 v25, v25, v25
	v_fmac_f32_e32 v25, v24, v24
	v_mul_f32_e32 v24, v27, v27
	v_fmac_f32_e32 v24, v26, v26
	v_add_f32_e32 v24, v25, v24
	v_add_f32_e32 v34, v36, v24
	v_lshl_add_u64 v[24:25], s[78:79], 0, v[96:97]
	v_lshl_add_u64 v[24:25], v[24:25], 0, s[34:35]
	v_lshl_add_u64 v[24:25], v[24:25], 0, s[14:15]
	v_cvt_pk_bf16_f32 v31, v26, v27
	v_lshl_add_u64 v[24:25], v[24:25], 0, v[200:201]
	global_store_dwordx4 v[24:25], v[28:31], off
	v_lshlrev_b32_e32 v26, 16, v72
	v_and_b32_e32 v27, 0xffff0000, v72
	v_lshlrev_b32_e32 v28, 16, v73
	v_and_b32_e32 v29, 0xffff0000, v73
	v_pk_fma_f32 v[22:23], v[22:23], 0.5, v[28:29] op_sel_hi:[1,0,1]
	v_pk_fma_f32 v[26:27], v[20:21], 0.5, v[26:27] op_sel_hi:[1,0,1]
	v_cvt_pk_bf16_f32 v21, v22, v23
	v_cvt_pk_bf16_f32 v20, v26, v27
	v_mul_f32_e32 v27, v27, v27
	v_mul_f32_e32 v23, v23, v23
	v_fmac_f32_e32 v27, v26, v26
	v_fmac_f32_e32 v23, v22, v22
	v_add_f32_e32 v22, v27, v23
	v_add_f32_e32 v28, v34, v22
	v_lshlrev_b32_e32 v22, 16, v74
	v_and_b32_e32 v23, 0xffff0000, v74
	v_lshlrev_b32_e32 v26, 16, v75
	v_and_b32_e32 v27, 0xffff0000, v75
	v_pk_fma_f32 v[16:17], v[16:17], 0.5, v[22:23] op_sel_hi:[1,0,1]
	v_pk_fma_f32 v[18:19], v[18:19], 0.5, v[26:27] op_sel_hi:[1,0,1]
	v_cvt_pk_bf16_f32 v22, v16, v17
	v_mul_f32_e32 v17, v17, v17
	v_cvt_pk_bf16_f32 v23, v18, v19
	v_fmac_f32_e32 v17, v16, v16
	v_mul_f32_e32 v16, v19, v19
	v_fmac_f32_e32 v16, v18, v18
	global_store_dwordx4 v[24:25], v[20:23], off offset:256
	v_lshlrev_b32_e32 v18, 16, v68
	v_and_b32_e32 v19, 0xffff0000, v68
	v_lshlrev_b32_e32 v20, 16, v69
	v_and_b32_e32 v21, 0xffff0000, v69
	v_pk_fma_f32 v[14:15], v[14:15], 0.5, v[20:21] op_sel_hi:[1,0,1]
	v_pk_fma_f32 v[18:19], v[12:13], 0.5, v[18:19] op_sel_hi:[1,0,1]
	v_cvt_pk_bf16_f32 v13, v14, v15
	v_cvt_pk_bf16_f32 v12, v18, v19
	v_mul_f32_e32 v19, v19, v19
	v_mul_f32_e32 v15, v15, v15
	v_fmac_f32_e32 v19, v18, v18
	v_fmac_f32_e32 v15, v14, v14
	v_add_f32_e32 v20, v19, v15
	v_lshlrev_b32_e32 v14, 16, v70
	v_and_b32_e32 v15, 0xffff0000, v70
	v_lshlrev_b32_e32 v18, 16, v71
	v_and_b32_e32 v19, 0xffff0000, v71
	v_pk_fma_f32 v[8:9], v[8:9], 0.5, v[14:15] op_sel_hi:[1,0,1]
	v_pk_fma_f32 v[10:11], v[10:11], 0.5, v[18:19] op_sel_hi:[1,0,1]
	v_cvt_pk_bf16_f32 v14, v8, v9
	v_mul_f32_e32 v9, v9, v9
	v_fmac_f32_e32 v9, v8, v8
	v_mul_f32_e32 v8, v11, v11
	v_fmac_f32_e32 v8, v10, v10
	v_add_f32_e32 v8, v9, v8
	v_add_f32_e32 v18, v20, v8
	v_lshl_add_u64 v[8:9], s[78:79], 0, v[94:95]
	v_lshl_add_u64 v[8:9], v[8:9], 0, s[34:35]
	v_lshl_add_u64 v[8:9], v[8:9], 0, s[14:15]
	v_cvt_pk_bf16_f32 v15, v10, v11
	v_lshl_add_u64 v[8:9], v[8:9], 0, v[200:201]
	global_store_dwordx4 v[8:9], v[12:15], off
	v_lshlrev_b32_e32 v10, 16, v64
	v_and_b32_e32 v11, 0xffff0000, v64
	v_lshlrev_b32_e32 v12, 16, v65
	v_and_b32_e32 v13, 0xffff0000, v65
	v_pk_fma_f32 v[6:7], v[6:7], 0.5, v[12:13] op_sel_hi:[1,0,1]
	v_pk_fma_f32 v[10:11], v[4:5], 0.5, v[10:11] op_sel_hi:[1,0,1]
	v_cvt_pk_bf16_f32 v5, v6, v7
	v_cvt_pk_bf16_f32 v4, v10, v11
	v_mul_f32_e32 v11, v11, v11
	v_mul_f32_e32 v7, v7, v7
	v_fmac_f32_e32 v11, v10, v10
	v_fmac_f32_e32 v7, v6, v6
	v_add_f32_e32 v6, v11, v7
	v_add_f32_e32 v12, v18, v6
	v_lshlrev_b32_e32 v6, 16, v66
	v_and_b32_e32 v7, 0xffff0000, v66
	v_lshlrev_b32_e32 v10, 16, v67
	v_and_b32_e32 v11, 0xffff0000, v67
	v_pk_fma_f32 v[0:1], v[0:1], 0.5, v[6:7] op_sel_hi:[1,0,1]
	v_pk_fma_f32 v[2:3], v[2:3], 0.5, v[10:11] op_sel_hi:[1,0,1]
	v_cvt_pk_bf16_f32 v6, v0, v1
	v_mul_f32_e32 v1, v1, v1
	v_fmac_f32_e32 v1, v0, v0
	v_mul_f32_e32 v0, v3, v3
	v_fmac_f32_e32 v0, v2, v2
	v_add_f32_e32 v48, v49, v48
	v_add_f32_e32 v32, v33, v32
	v_add_f32_e32 v16, v17, v16
	v_add_f32_e32 v0, v1, v0
	v_add_f32_e32 v48, v48, v60
	v_add_f32_e32 v32, v32, v44
	v_add_f32_e32 v16, v16, v28
	v_add_f32_e32 v0, v0, v12
	ds_bpermute_b32 v49, v167, v48
	ds_bpermute_b32 v33, v167, v32
	ds_bpermute_b32 v17, v167, v16
	ds_bpermute_b32 v1, v167, v0
	v_cvt_pk_bf16_f32 v7, v2, v3
	s_waitcnt lgkmcnt(3)
	v_add_f32_e32 v48, v48, v49
	s_waitcnt lgkmcnt(2)
	v_add_f32_e32 v32, v32, v33
	s_waitcnt lgkmcnt(1)
	v_add_f32_e32 v16, v16, v17
	s_waitcnt lgkmcnt(0)
	v_add_f32_e32 v0, v0, v1
	ds_bpermute_b32 v49, v166, v48
	ds_bpermute_b32 v33, v166, v32
	ds_bpermute_b32 v17, v166, v16
	ds_bpermute_b32 v1, v166, v0
	global_store_dwordx4 v[8:9], v[4:7], off offset:256
	s_and_saveexec_b64 s[34:35], s[2:3]
	s_cbranch_execz .LBB0_269
	s_waitcnt lgkmcnt(3)
	v_add_f32_e32 v3, v48, v49
	s_waitcnt lgkmcnt(0)
	v_add_f32_e32 v0, v0, v1
	v_add_f32_e32 v1, v16, v17
	v_add_f32_e32 v2, v32, v33
	global_atomic_add_f32 v[92:93], v3, off offset:512
	global_atomic_add_f32 v[92:93], v2, off offset:576
	global_atomic_add_f32 v[92:93], v1, off offset:640
	global_atomic_add_f32 v[92:93], v0, off offset:704

.LBB0_1555:
	s_mov_b32 s98, 0x40000
	s_mov_b32 s99, 0
	s_lshl_b32 s20, s18, 8
	s_lshl_b32 s18, s19, 8
	v_add_u32_e32 v162, s20, v170
	s_ashr_i32 s19, s18, 31
	s_lshl_b64 s[18:19], s[18:19], 1
	v_ashrrev_i32_e32 v163, 31, v162
	v_lshl_add_u64 v[164:165], v[150:151], 0, s[18:19]
	v_lshlrev_b64 v[128:129], 11, v[162:163]
	v_lshl_add_u64 v[130:131], v[164:165], 0, v[128:129]
	v_lshl_add_u64 v[222:223], v[130:131], 0, s[98:99]
	global_load_dwordx4 v[178:181], v[130:131], off
	global_load_dwordx4 v[182:185], v[130:131], off offset:256
	global_load_dwordx4 v[210:213], v[222:223], off
	global_load_dwordx4 v[214:217], v[222:223], off offset:256
	v_and_b32_e32 v131, 64, v175
	v_xor_b32_e32 v130, 16, v175
	v_add_u32_e32 v131, 64, v131
	v_cmp_lt_i32_e32 vcc, v130, v131
	v_xor_b32_e32 v132, 32, v175
	v_or_b32_e32 v134, 48, v162
	v_cndmask_b32_e32 v133, v175, v130, vcc
	v_or_b32_e32 v130, 16, v162
	v_cmp_lt_i32_e32 vcc, v132, v131
	v_ashrrev_i32_e32 v131, 31, v130
	v_lshlrev_b64 v[198:199], 11, v[130:131]
	v_lshl_add_u64 v[130:131], v[164:165], 0, v[198:199]
	v_lshl_add_u64 v[222:223], v[130:131], 0, s[98:99]
	global_load_dwordx4 v[186:189], v[130:131], off
	v_cndmask_b32_e32 v135, v175, v132, vcc
	v_or_b32_e32 v132, 32, v162
	v_lshlrev_b32_e32 v176, 2, v133
	v_ashrrev_i32_e32 v133, 31, v132
	v_lshlrev_b32_e32 v163, 2, v135
	v_ashrrev_i32_e32 v135, 31, v134
	v_lshlrev_b64 v[168:169], 11, v[132:133]
	v_lshlrev_b64 v[166:167], 11, v[134:135]
	v_lshl_add_u64 v[128:129], s[78:79], 0, v[128:129]
	v_lshl_add_u64 v[132:133], v[164:165], 0, v[168:169]
	v_lshl_add_u64 v[200:201], v[164:165], 0, v[166:167]
	v_lshl_add_u64 v[202:203], v[128:129], 0, s[18:19]
	global_load_dwordx4 v[190:193], v[130:131], off offset:256
	global_load_dwordx4 v[218:221], v[222:223], off
	global_load_dwordx4 v[226:229], v[222:223], off offset:256
	v_lshl_add_u64 v[222:223], v[132:133], 0, s[98:99]
	global_load_dwordx4 v[194:197], v[132:133], off
	global_load_dwordx4 v[136:139], v[132:133], off offset:256
	global_load_dwordx4 v[236:239], v[222:223], off
	global_load_dwordx4 v[240:243], v[222:223], off offset:256
	s_nop 0
	v_lshl_add_u64 v[222:223], v[200:201], 0, s[98:99]
	global_load_dwordx4 v[132:135], v[200:201], off
	global_load_dwordx4 v[128:131], v[200:201], off offset:256
	global_load_dwordx4 v[246:249], v[222:223], off
	global_load_dwordx4 v[250:253], v[222:223], off offset:256
	v_lshl_add_u64 v[200:201], v[202:203], 0, s[0:1]
	v_lshl_add_u64 v[200:201], v[200:201], 0, v[148:149]
	s_ashr_i32 s21, s20, 31
	s_waitcnt vmcnt(14)
	v_lshlrev_b32_e32 v202, 16, v178
	v_and_b32_e32 v203, 0xffff0000, v178
	v_lshlrev_b32_e32 v178, 16, v179
	v_and_b32_e32 v179, 0xffff0000, v179
	v_lshlrev_b32_e32 v204, 16, v180
	v_and_b32_e32 v205, 0xffff0000, v180
	v_lshlrev_b32_e32 v180, 16, v181
	v_and_b32_e32 v181, 0xffff0000, v181
	v_lshlrev_b32_e32 v206, 16, v182
	v_and_b32_e32 v207, 0xffff0000, v182
	v_lshlrev_b32_e32 v182, 16, v183
	v_and_b32_e32 v183, 0xffff0000, v183
	v_lshlrev_b32_e32 v208, 16, v184
	v_and_b32_e32 v209, 0xffff0000, v184
	v_lshlrev_b32_e32 v184, 16, v185
	v_and_b32_e32 v185, 0xffff0000, v185
	v_pk_add_f32 v[126:127], v[126:127], v[178:179]
	v_pk_add_f32 v[124:125], v[124:125], v[202:203]
	v_pk_add_f32 v[122:123], v[122:123], v[180:181]
	v_pk_add_f32 v[120:121], v[120:121], v[204:205]
	v_pk_add_f32 v[118:119], v[118:119], v[182:183]
	v_pk_add_f32 v[178:179], v[116:117], v[206:207]
	v_pk_add_f32 v[180:181], v[114:115], v[184:185]
	v_pk_add_f32 v[182:183], v[112:113], v[208:209]
	v_cvt_pk_bf16_f32 v112, v124, v125
	v_mul_f32_e32 v117, v125, v125
	v_mul_f32_e32 v125, v127, v127
	v_cvt_pk_bf16_f32 v114, v120, v121
	v_cvt_pk_bf16_f32 v115, v122, v123
	v_mul_f32_e32 v121, v121, v121
	v_mul_f32_e32 v123, v123, v123
	v_cvt_pk_bf16_f32 v113, v126, v127
	v_mul_f32_e32 v127, v179, v179
	v_mul_f32_e32 v177, v119, v119
	v_fmac_f32_e32 v117, v124, v124
	v_fmac_f32_e32 v125, v126, v126
	v_fmac_f32_e32 v121, v120, v120
	v_fmac_f32_e32 v123, v122, v122
	global_store_dwordx4 v[200:201], v[112:115], off
	v_fmac_f32_e32 v127, v178, v178
	v_fmac_f32_e32 v177, v118, v118
	v_add_f32_e32 v112, v117, v125
	v_add_f32_e32 v113, v121, v123
	v_cvt_pk_bf16_f32 v116, v178, v179
	v_add_f32_e32 v114, v127, v177
	v_add_f32_e32 v112, v112, v113
	v_cvt_pk_bf16_f32 v117, v118, v119
	v_cvt_pk_bf16_f32 v118, v182, v183
	v_cvt_pk_bf16_f32 v119, v180, v181
	v_add_f32_e32 v112, v112, v114
	global_store_dwordx4 v[200:201], v[116:119], off offset:256
	s_waitcnt vmcnt(12)
	v_lshlrev_b32_e32 v114, 16, v186
	v_and_b32_e32 v115, 0xffff0000, v186
	v_lshlrev_b32_e32 v116, 16, v187
	v_and_b32_e32 v117, 0xffff0000, v187
	v_pk_add_f32 v[110:111], v[110:111], v[116:117]
	v_pk_add_f32 v[114:115], v[108:109], v[114:115]
	v_cvt_pk_bf16_f32 v109, v110, v111
	v_cvt_pk_bf16_f32 v108, v114, v115
	v_mul_f32_e32 v115, v115, v115
	v_mul_f32_e32 v111, v111, v111
	v_fmac_f32_e32 v115, v114, v114
	v_fmac_f32_e32 v111, v110, v110
	v_add_f32_e32 v116, v115, v111
	v_lshlrev_b32_e32 v110, 16, v188
	v_and_b32_e32 v111, 0xffff0000, v188
	v_lshlrev_b32_e32 v114, 16, v189
	v_and_b32_e32 v115, 0xffff0000, v189
	v_pk_add_f32 v[104:105], v[104:105], v[110:111]
	v_pk_add_f32 v[106:107], v[106:107], v[114:115]
	v_cvt_pk_bf16_f32 v110, v104, v105
	v_mul_f32_e32 v105, v105, v105
	v_fmac_f32_e32 v105, v104, v104
	v_mul_f32_e32 v104, v107, v107
	v_fmac_f32_e32 v104, v106, v106
	v_add_f32_e32 v104, v105, v104
	v_add_f32_e32 v114, v116, v104
	v_lshl_add_u64 v[104:105], s[78:79], 0, v[198:199]
	v_lshl_add_u64 v[104:105], v[104:105], 0, s[18:19]
	v_lshl_add_u64 v[104:105], v[104:105], 0, s[0:1]
	v_cvt_pk_bf16_f32 v111, v106, v107
	v_lshl_add_u64 v[104:105], v[104:105], 0, v[148:149]
	v_lshlrev_b32_e32 v106, 16, v190
	v_and_b32_e32 v107, 0xffff0000, v190
	global_store_dwordx4 v[104:105], v[108:111], off
	v_pk_add_f32 v[106:107], v[100:101], v[106:107]
	v_mul_f32_e32 v179, v183, v183
	v_lshlrev_b32_e32 v108, 16, v191
	v_and_b32_e32 v109, 0xffff0000, v191
	v_pk_add_f32 v[102:103], v[102:103], v[108:109]
	v_mul_f32_e32 v101, v107, v107
	v_cvt_pk_bf16_f32 v100, v106, v107
	v_fmac_f32_e32 v101, v106, v106
	v_mul_f32_e32 v106, v103, v103
	v_fmac_f32_e32 v106, v102, v102
	v_add_f32_e32 v101, v101, v106
	v_lshlrev_b32_e32 v106, 16, v192
	v_and_b32_e32 v107, 0xffff0000, v192
	v_lshlrev_b32_e32 v108, 16, v193
	v_and_b32_e32 v109, 0xffff0000, v193
	v_pk_add_f32 v[98:99], v[98:99], v[108:109]
	v_pk_add_f32 v[96:97], v[96:97], v[106:107]
	v_mul_f32_e32 v107, v99, v99
	v_mul_f32_e32 v106, v97, v97
	v_fmac_f32_e32 v106, v96, v96
	v_fmac_f32_e32 v107, v98, v98
	v_add_f32_e32 v101, v114, v101
	v_add_f32_e32 v106, v106, v107
	v_add_f32_e32 v106, v106, v101
	v_cvt_pk_bf16_f32 v101, v102, v103
	v_cvt_pk_bf16_f32 v102, v96, v97
	v_cvt_pk_bf16_f32 v103, v98, v99
	global_store_dwordx4 v[104:105], v[100:103], off offset:256
	s_waitcnt vmcnt(10)
	v_lshlrev_b32_e32 v98, 16, v194
	v_and_b32_e32 v99, 0xffff0000, v194
	v_lshlrev_b32_e32 v100, 16, v195
	v_and_b32_e32 v101, 0xffff0000, v195
	v_pk_add_f32 v[94:95], v[94:95], v[100:101]
	v_pk_add_f32 v[98:99], v[92:93], v[98:99]
	v_cvt_pk_bf16_f32 v93, v94, v95
	v_cvt_pk_bf16_f32 v92, v98, v99
	v_mul_f32_e32 v99, v99, v99
	v_mul_f32_e32 v95, v95, v95
	v_fmac_f32_e32 v99, v98, v98
	v_fmac_f32_e32 v95, v94, v94
	v_add_f32_e32 v100, v99, v95
	v_lshlrev_b32_e32 v94, 16, v196
	v_and_b32_e32 v95, 0xffff0000, v196
	v_lshlrev_b32_e32 v98, 16, v197
	v_and_b32_e32 v99, 0xffff0000, v197
	v_pk_add_f32 v[88:89], v[88:89], v[94:95]
	v_pk_add_f32 v[90:91], v[90:91], v[98:99]
	v_cvt_pk_bf16_f32 v94, v88, v89
	v_mul_f32_e32 v89, v89, v89
	v_fmac_f32_e32 v89, v88, v88
	v_mul_f32_e32 v88, v91, v91
	v_fmac_f32_e32 v88, v90, v90
	v_add_f32_e32 v88, v89, v88
	v_add_f32_e32 v98, v100, v88
	v_lshl_add_u64 v[88:89], s[78:79], 0, v[168:169]
	v_lshl_add_u64 v[88:89], v[88:89], 0, s[18:19]
	v_lshl_add_u64 v[88:89], v[88:89], 0, s[0:1]
	v_cvt_pk_bf16_f32 v95, v90, v91
	v_lshl_add_u64 v[88:89], v[88:89], 0, v[148:149]
	v_lshlrev_b32_e32 v90, 16, v136
	v_and_b32_e32 v91, 0xffff0000, v136
	global_store_dwordx4 v[88:89], v[92:95], off
	v_pk_add_f32 v[90:91], v[84:85], v[90:91]
	v_mul_f32_e32 v113, v181, v181
	v_lshlrev_b32_e32 v92, 16, v137
	v_and_b32_e32 v93, 0xffff0000, v137
	v_pk_add_f32 v[86:87], v[86:87], v[92:93]
	v_mul_f32_e32 v85, v91, v91
	v_cvt_pk_bf16_f32 v84, v90, v91
	v_fmac_f32_e32 v85, v90, v90
	v_mul_f32_e32 v90, v87, v87
	v_fmac_f32_e32 v90, v86, v86
	v_add_f32_e32 v85, v85, v90
	v_lshlrev_b32_e32 v90, 16, v138
	v_and_b32_e32 v91, 0xffff0000, v138
	v_lshlrev_b32_e32 v92, 16, v139
	v_and_b32_e32 v93, 0xffff0000, v139
	v_pk_add_f32 v[82:83], v[82:83], v[92:93]
	v_pk_add_f32 v[80:81], v[80:81], v[90:91]
	v_mul_f32_e32 v91, v83, v83
	v_mul_f32_e32 v90, v81, v81
	v_fmac_f32_e32 v90, v80, v80
	v_fmac_f32_e32 v91, v82, v82
	v_add_f32_e32 v85, v98, v85
	v_add_f32_e32 v90, v90, v91
	v_add_f32_e32 v90, v90, v85
	v_cvt_pk_bf16_f32 v85, v86, v87
	v_cvt_pk_bf16_f32 v86, v80, v81
	v_cvt_pk_bf16_f32 v87, v82, v83
	global_store_dwordx4 v[88:89], v[84:87], off offset:256
	s_waitcnt vmcnt(8)
	v_lshlrev_b32_e32 v82, 16, v132
	v_and_b32_e32 v83, 0xffff0000, v132
	v_lshlrev_b32_e32 v84, 16, v133
	v_and_b32_e32 v85, 0xffff0000, v133
	v_pk_add_f32 v[78:79], v[78:79], v[84:85]
	v_pk_add_f32 v[82:83], v[76:77], v[82:83]
	v_cvt_pk_bf16_f32 v77, v78, v79
	v_cvt_pk_bf16_f32 v76, v82, v83
	v_mul_f32_e32 v83, v83, v83
	v_mul_f32_e32 v79, v79, v79
	v_fmac_f32_e32 v83, v82, v82
	v_fmac_f32_e32 v79, v78, v78
	v_add_f32_e32 v84, v83, v79
	v_lshlrev_b32_e32 v78, 16, v134
	v_and_b32_e32 v79, 0xffff0000, v134
	v_lshlrev_b32_e32 v82, 16, v135
	v_and_b32_e32 v83, 0xffff0000, v135
	v_pk_add_f32 v[72:73], v[72:73], v[78:79]
	v_pk_add_f32 v[74:75], v[74:75], v[82:83]
	v_cvt_pk_bf16_f32 v78, v72, v73
	v_mul_f32_e32 v73, v73, v73
	v_fmac_f32_e32 v73, v72, v72
	v_mul_f32_e32 v72, v75, v75
	v_cvt_pk_bf16_f32 v79, v74, v75
	v_fmac_f32_e32 v72, v74, v74
	v_lshlrev_b32_e32 v74, 16, v128
	v_and_b32_e32 v75, 0xffff0000, v128
	v_lshlrev_b32_e32 v82, 16, v129
	v_and_b32_e32 v83, 0xffff0000, v129
	v_pk_add_f32 v[70:71], v[70:71], v[82:83]
	v_pk_add_f32 v[68:69], v[68:69], v[74:75]
	v_mul_f32_e32 v75, v71, v71
	v_mul_f32_e32 v74, v69, v69
	v_add_f32_e32 v72, v73, v72
	v_fmac_f32_e32 v74, v68, v68
	v_fmac_f32_e32 v75, v70, v70
	v_add_f32_e32 v84, v84, v72
	v_add_f32_e32 v74, v74, v75
	v_add_f32_e32 v84, v84, v74
	v_lshlrev_b32_e32 v74, 16, v130
	v_and_b32_e32 v75, 0xffff0000, v130
	v_lshlrev_b32_e32 v82, 16, v131
	v_and_b32_e32 v83, 0xffff0000, v131
	v_pk_add_f32 v[82:83], v[66:67], v[82:83]
	v_pk_add_f32 v[74:75], v[64:65], v[74:75]
	v_mul_f32_e32 v65, v83, v83
	v_mul_f32_e32 v64, v75, v75
	v_fmac_f32_e32 v179, v182, v182
	v_fmac_f32_e32 v113, v180, v180
	v_fmac_f32_e32 v64, v74, v74
	v_fmac_f32_e32 v65, v82, v82
	v_add_f32_e32 v113, v179, v113
	v_add_f32_e32 v64, v64, v65
	v_add_f32_e32 v112, v113, v112
	v_add_f32_e32 v64, v64, v84
	ds_bpermute_b32 v113, v176, v112
	ds_bpermute_b32 v107, v176, v106
	ds_bpermute_b32 v91, v176, v90
	ds_bpermute_b32 v65, v176, v64
	v_lshl_add_u64 v[72:73], s[78:79], 0, v[166:167]
	s_waitcnt lgkmcnt(3)
	v_add_f32_e32 v112, v112, v113
	s_waitcnt lgkmcnt(2)
	v_add_f32_e32 v96, v106, v107
	s_waitcnt lgkmcnt(1)
	v_add_f32_e32 v80, v90, v91
	s_waitcnt lgkmcnt(0)
	v_add_f32_e32 v64, v64, v65
	ds_bpermute_b32 v113, v163, v112
	ds_bpermute_b32 v97, v163, v96
	ds_bpermute_b32 v81, v163, v80
	ds_bpermute_b32 v65, v163, v64
	v_lshl_add_u64 v[72:73], v[72:73], 0, s[18:19]
	v_lshl_add_u64 v[72:73], v[72:73], 0, s[0:1]
	v_lshl_add_u64 v[72:73], v[72:73], 0, v[148:149]
	global_store_dwordx4 v[72:73], v[76:79], off
	v_cvt_pk_bf16_f32 v66, v68, v69
	v_cvt_pk_bf16_f32 v67, v70, v71
	v_cvt_pk_bf16_f32 v68, v74, v75
	v_cvt_pk_bf16_f32 v69, v82, v83
	v_lshl_add_u64 v[76:77], s[20:21], 2, v[152:153]
	global_store_dwordx4 v[72:73], v[66:69], off offset:256
	s_and_saveexec_b64 s[20:21], s[2:3]
	s_cbranch_execz .LBB0_1557
	s_waitcnt lgkmcnt(3)
	v_add_f32_e32 v67, v112, v113
	s_waitcnt lgkmcnt(0)
	v_add_f32_e32 v64, v64, v65
	v_add_f32_e32 v65, v80, v81
	v_add_f32_e32 v66, v96, v97
	global_atomic_add_f32 v[76:77], v67, off
	global_atomic_add_f32 v[76:77], v66, off offset:64
	global_atomic_add_f32 v[76:77], v65, off offset:128
	global_atomic_add_f32 v[76:77], v64, off offset:192
.LBB0_1557:
	s_or_b64 exec, exec, s[20:21]
	s_waitcnt vmcnt(8)
	v_add_u32_e32 v64, 0x80, v162
	s_waitcnt lgkmcnt(0)
	v_ashrrev_i32_e32 v65, 31, v64
	v_lshlrev_b64 v[64:65], 11, v[64:65]
	v_lshl_add_u64 v[66:67], v[164:165], 0, v[64:65]
	v_mov_b32_e32 v82, v210
	v_mov_b32_e32 v83, v211
	v_mov_b32_e32 v84, v212
	v_mov_b32_e32 v85, v213
	v_mov_b32_e32 v86, v214
	v_mov_b32_e32 v87, v215
	v_mov_b32_e32 v88, v216
	v_mov_b32_e32 v89, v217
	v_add_u32_e32 v66, 0x90, v162
	v_ashrrev_i32_e32 v67, 31, v66
	v_lshlrev_b64 v[102:103], 11, v[66:67]
	v_lshl_add_u64 v[66:67], v[164:165], 0, v[102:103]
	v_mov_b32_e32 v90, v218
	v_mov_b32_e32 v91, v219
	v_mov_b32_e32 v92, v220
	v_mov_b32_e32 v93, v221
	v_add_u32_e32 v68, 0xa0, v162
	v_add_u32_e32 v70, 0xb0, v162
	v_ashrrev_i32_e32 v69, 31, v68
	v_ashrrev_i32_e32 v71, 31, v70
	v_lshlrev_b64 v[80:81], 11, v[68:69]
	v_lshlrev_b64 v[78:79], 11, v[70:71]
	v_lshl_add_u64 v[68:69], v[164:165], 0, v[80:81]
	v_lshl_add_u64 v[104:105], v[164:165], 0, v[78:79]
	v_lshl_add_u64 v[106:107], s[78:79], 0, v[64:65]
	v_mov_b32_e32 v94, v226
	v_mov_b32_e32 v95, v227
	v_mov_b32_e32 v96, v228
	v_mov_b32_e32 v97, v229
	v_mov_b32_e32 v98, v236
	v_mov_b32_e32 v99, v237
	v_mov_b32_e32 v100, v238
	v_mov_b32_e32 v101, v239
	v_mov_b32_e32 v72, v240
	v_mov_b32_e32 v73, v241
	v_mov_b32_e32 v74, v242
	v_mov_b32_e32 v75, v243
	s_nop 0
	v_mov_b32_e32 v68, v246
	v_mov_b32_e32 v69, v247
	v_mov_b32_e32 v70, v248
	v_mov_b32_e32 v71, v249
	v_mov_b32_e32 v64, v250
	v_mov_b32_e32 v65, v251
	v_mov_b32_e32 v66, v252
	v_mov_b32_e32 v67, v253
	v_lshl_add_u64 v[104:105], v[106:107], 0, s[18:19]
	v_lshl_add_u64 v[104:105], v[104:105], 0, s[0:1]
	v_lshl_add_u64 v[104:105], v[104:105], 0, v[148:149]
	v_lshlrev_b32_e32 v106, 16, v82
	v_and_b32_e32 v107, 0xffff0000, v82
	v_lshlrev_b32_e32 v82, 16, v83
	v_and_b32_e32 v83, 0xffff0000, v83
	v_lshlrev_b32_e32 v108, 16, v84
	v_and_b32_e32 v109, 0xffff0000, v84
	v_lshlrev_b32_e32 v84, 16, v85
	v_and_b32_e32 v85, 0xffff0000, v85
	v_lshlrev_b32_e32 v110, 16, v86
	v_and_b32_e32 v111, 0xffff0000, v86
	v_lshlrev_b32_e32 v86, 16, v87
	v_and_b32_e32 v87, 0xffff0000, v87
	v_lshlrev_b32_e32 v112, 16, v88
	v_and_b32_e32 v113, 0xffff0000, v88
	v_lshlrev_b32_e32 v88, 16, v89
	v_and_b32_e32 v89, 0xffff0000, v89
	v_pk_add_f32 v[62:63], v[62:63], v[82:83]
	v_pk_add_f32 v[60:61], v[60:61], v[106:107]
	v_pk_add_f32 v[58:59], v[58:59], v[84:85]
	v_pk_add_f32 v[56:57], v[56:57], v[108:109]
	v_lshlrev_b32_e32 v114, 16, v90
	v_and_b32_e32 v115, 0xffff0000, v90
	v_lshlrev_b32_e32 v90, 16, v91
	v_and_b32_e32 v91, 0xffff0000, v91
	v_pk_add_f32 v[82:83], v[50:51], v[86:87]
	v_pk_add_f32 v[84:85], v[48:49], v[110:111]
	v_pk_add_f32 v[86:87], v[46:47], v[88:89]
	v_pk_add_f32 v[88:89], v[44:45], v[112:113]
	v_cvt_pk_bf16_f32 v44, v60, v61
	v_cvt_pk_bf16_f32 v45, v62, v63
	v_cvt_pk_bf16_f32 v46, v56, v57
	v_cvt_pk_bf16_f32 v47, v58, v59
	v_pk_add_f32 v[54:55], v[54:55], v[90:91]
	v_cvt_pk_bf16_f32 v48, v84, v85
	v_cvt_pk_bf16_f32 v49, v82, v83
	v_cvt_pk_bf16_f32 v50, v88, v89
	v_cvt_pk_bf16_f32 v51, v86, v87
	global_store_dwordx4 v[104:105], v[44:47], off
	global_store_dwordx4 v[104:105], v[48:51], off offset:256
	v_pk_add_f32 v[90:91], v[52:53], v[114:115]
	v_lshlrev_b32_e32 v46, 16, v92
	v_and_b32_e32 v47, 0xffff0000, v92
	v_cvt_pk_bf16_f32 v53, v54, v55
	v_mul_f32_e32 v55, v55, v55
	v_lshlrev_b32_e32 v48, 16, v93
	v_and_b32_e32 v49, 0xffff0000, v93
	v_pk_add_f32 v[40:41], v[40:41], v[46:47]
	v_cvt_pk_bf16_f32 v52, v90, v91
	v_mul_f32_e32 v91, v91, v91
	v_fmac_f32_e32 v55, v54, v54
	v_pk_add_f32 v[42:43], v[42:43], v[48:49]
	v_cvt_pk_bf16_f32 v54, v40, v41
	v_mul_f32_e32 v41, v41, v41
	v_fmac_f32_e32 v91, v90, v90
	v_fmac_f32_e32 v41, v40, v40
	v_mul_f32_e32 v40, v43, v43
	v_add_f32_e32 v50, v91, v55
	v_cvt_pk_bf16_f32 v55, v42, v43
	v_fmac_f32_e32 v40, v42, v42
	v_lshlrev_b32_e32 v42, 16, v94
	v_and_b32_e32 v43, 0xffff0000, v94
	v_lshlrev_b32_e32 v46, 16, v95
	v_and_b32_e32 v47, 0xffff0000, v95
	v_pk_add_f32 v[42:43], v[36:37], v[42:43]
	v_pk_add_f32 v[38:39], v[38:39], v[46:47]
	v_mul_f32_e32 v37, v43, v43
	v_cvt_pk_bf16_f32 v36, v42, v43
	v_fmac_f32_e32 v37, v42, v42
	v_mul_f32_e32 v42, v39, v39
	v_fmac_f32_e32 v42, v38, v38
	v_add_f32_e32 v37, v37, v42
	v_lshlrev_b32_e32 v42, 16, v96
	v_and_b32_e32 v43, 0xffff0000, v96
	v_lshlrev_b32_e32 v46, 16, v97
	v_and_b32_e32 v47, 0xffff0000, v97
	v_add_f32_e32 v40, v41, v40
	v_pk_add_f32 v[34:35], v[34:35], v[46:47]
	v_pk_add_f32 v[32:33], v[32:33], v[42:43]
	v_add_f32_e32 v48, v50, v40
	v_lshl_add_u64 v[40:41], s[78:79], 0, v[102:103]
	v_mul_f32_e32 v42, v33, v33
	v_mul_f32_e32 v43, v35, v35
	v_lshl_add_u64 v[40:41], v[40:41], 0, s[18:19]
	v_fmac_f32_e32 v42, v32, v32
	v_fmac_f32_e32 v43, v34, v34
	v_lshl_add_u64 v[40:41], v[40:41], 0, s[0:1]
	v_add_f32_e32 v37, v48, v37
	v_add_f32_e32 v42, v42, v43
	v_lshl_add_u64 v[40:41], v[40:41], 0, v[148:149]
	v_add_f32_e32 v42, v42, v37
	v_cvt_pk_bf16_f32 v37, v38, v39
	v_cvt_pk_bf16_f32 v38, v32, v33
	v_cvt_pk_bf16_f32 v39, v34, v35
	global_store_dwordx4 v[40:41], v[36:39], off offset:256
	v_lshlrev_b32_e32 v34, 16, v98
	v_and_b32_e32 v35, 0xffff0000, v98
	v_lshlrev_b32_e32 v36, 16, v99
	v_and_b32_e32 v37, 0xffff0000, v99
	v_pk_add_f32 v[30:31], v[30:31], v[36:37]
	v_pk_add_f32 v[34:35], v[28:29], v[34:35]
	v_cvt_pk_bf16_f32 v29, v30, v31
	v_cvt_pk_bf16_f32 v28, v34, v35
	v_mul_f32_e32 v35, v35, v35
	v_mul_f32_e32 v31, v31, v31
	v_fmac_f32_e32 v35, v34, v34
	v_fmac_f32_e32 v31, v30, v30
	v_add_f32_e32 v36, v35, v31
	v_lshlrev_b32_e32 v30, 16, v100
	v_and_b32_e32 v31, 0xffff0000, v100
	v_lshlrev_b32_e32 v34, 16, v101
	v_and_b32_e32 v35, 0xffff0000, v101
	v_pk_add_f32 v[24:25], v[24:25], v[30:31]
	v_pk_add_f32 v[26:27], v[26:27], v[34:35]
	v_cvt_pk_bf16_f32 v30, v24, v25
	v_mul_f32_e32 v25, v25, v25
	v_fmac_f32_e32 v25, v24, v24
	v_mul_f32_e32 v24, v27, v27
	v_fmac_f32_e32 v24, v26, v26
	v_add_f32_e32 v24, v25, v24
	v_add_f32_e32 v34, v36, v24
	v_lshl_add_u64 v[24:25], s[78:79], 0, v[80:81]
	v_lshl_add_u64 v[24:25], v[24:25], 0, s[18:19]
	v_lshl_add_u64 v[24:25], v[24:25], 0, s[0:1]
	v_cvt_pk_bf16_f32 v31, v26, v27
	v_lshl_add_u64 v[24:25], v[24:25], 0, v[148:149]
	v_lshlrev_b32_e32 v26, 16, v72
	v_and_b32_e32 v27, 0xffff0000, v72
	global_store_dwordx4 v[24:25], v[28:31], off
	v_pk_add_f32 v[26:27], v[20:21], v[26:27]
	v_mul_f32_e32 v61, v61, v61
	v_lshlrev_b32_e32 v28, 16, v73
	v_and_b32_e32 v29, 0xffff0000, v73
	v_pk_add_f32 v[22:23], v[22:23], v[28:29]
	v_mul_f32_e32 v21, v27, v27
	v_cvt_pk_bf16_f32 v20, v26, v27
	v_fmac_f32_e32 v21, v26, v26
	v_mul_f32_e32 v26, v23, v23
	v_fmac_f32_e32 v26, v22, v22
	v_add_f32_e32 v21, v21, v26
	v_lshlrev_b32_e32 v26, 16, v74
	v_and_b32_e32 v27, 0xffff0000, v74
	v_lshlrev_b32_e32 v28, 16, v75
	v_and_b32_e32 v29, 0xffff0000, v75
	v_pk_add_f32 v[18:19], v[18:19], v[28:29]
	v_pk_add_f32 v[16:17], v[16:17], v[26:27]
	v_mul_f32_e32 v27, v19, v19
	v_mul_f32_e32 v26, v17, v17
	v_fmac_f32_e32 v26, v16, v16
	v_fmac_f32_e32 v27, v18, v18
	v_add_f32_e32 v21, v34, v21
	v_add_f32_e32 v26, v26, v27
	v_add_f32_e32 v26, v26, v21
	v_cvt_pk_bf16_f32 v21, v22, v23
	v_cvt_pk_bf16_f32 v22, v16, v17
	v_cvt_pk_bf16_f32 v23, v18, v19
	global_store_dwordx4 v[24:25], v[20:23], off offset:256
	v_lshlrev_b32_e32 v18, 16, v68
	v_and_b32_e32 v19, 0xffff0000, v68
	v_lshlrev_b32_e32 v20, 16, v69
	v_and_b32_e32 v21, 0xffff0000, v69
	v_pk_add_f32 v[14:15], v[14:15], v[20:21]
	v_pk_add_f32 v[18:19], v[12:13], v[18:19]
	v_cvt_pk_bf16_f32 v13, v14, v15
	v_cvt_pk_bf16_f32 v12, v18, v19
	v_mul_f32_e32 v19, v19, v19
	v_mul_f32_e32 v15, v15, v15
	v_fmac_f32_e32 v19, v18, v18
	v_fmac_f32_e32 v15, v14, v14
	v_add_f32_e32 v20, v19, v15
	v_lshlrev_b32_e32 v14, 16, v70
	v_and_b32_e32 v15, 0xffff0000, v70
	v_lshlrev_b32_e32 v18, 16, v71
	v_and_b32_e32 v19, 0xffff0000, v71
	v_pk_add_f32 v[8:9], v[8:9], v[14:15]
	v_pk_add_f32 v[10:11], v[10:11], v[18:19]
	v_cvt_pk_bf16_f32 v14, v8, v9
	v_mul_f32_e32 v9, v9, v9
	v_fmac_f32_e32 v9, v8, v8
	v_mul_f32_e32 v8, v11, v11
	v_cvt_pk_bf16_f32 v15, v10, v11
	v_fmac_f32_e32 v8, v10, v10
	v_lshlrev_b32_e32 v10, 16, v64
	v_and_b32_e32 v11, 0xffff0000, v64
	v_lshlrev_b32_e32 v18, 16, v65
	v_and_b32_e32 v19, 0xffff0000, v65
	v_pk_add_f32 v[6:7], v[6:7], v[18:19]
	v_pk_add_f32 v[4:5], v[4:5], v[10:11]
	v_mul_f32_e32 v11, v7, v7
	v_mul_f32_e32 v10, v5, v5
	v_add_f32_e32 v8, v9, v8
	v_fmac_f32_e32 v10, v4, v4
	v_fmac_f32_e32 v11, v6, v6
	v_add_f32_e32 v20, v20, v8
	v_add_f32_e32 v10, v10, v11
	v_mul_f32_e32 v63, v63, v63
	v_mul_f32_e32 v57, v57, v57
	v_mul_f32_e32 v59, v59, v59
	v_add_f32_e32 v20, v20, v10
	v_lshlrev_b32_e32 v10, 16, v66
	v_and_b32_e32 v11, 0xffff0000, v66
	v_lshlrev_b32_e32 v18, 16, v67
	v_and_b32_e32 v19, 0xffff0000, v67
	v_mul_f32_e32 v85, v85, v85
	v_mul_f32_e32 v83, v83, v83
	v_fmac_f32_e32 v61, v60, v60
	v_fmac_f32_e32 v63, v62, v62
	v_fmac_f32_e32 v57, v56, v56
	v_fmac_f32_e32 v59, v58, v58
	v_pk_add_f32 v[18:19], v[2:3], v[18:19]
	v_pk_add_f32 v[10:11], v[0:1], v[10:11]
	v_mul_f32_e32 v89, v89, v89
	v_mul_f32_e32 v87, v87, v87
	v_fmac_f32_e32 v85, v84, v84
	v_fmac_f32_e32 v83, v82, v82
	v_add_f32_e32 v56, v61, v63
	v_add_f32_e32 v57, v57, v59
	v_mul_f32_e32 v0, v11, v11
	v_mul_f32_e32 v1, v19, v19
	v_fmac_f32_e32 v89, v88, v88
	v_fmac_f32_e32 v87, v86, v86
	v_add_f32_e32 v58, v85, v83
	v_add_f32_e32 v56, v56, v57
	v_fmac_f32_e32 v0, v10, v10
	v_fmac_f32_e32 v1, v18, v18
	v_add_f32_e32 v59, v89, v87
	v_add_f32_e32 v56, v56, v58
	v_add_f32_e32 v0, v0, v1
	v_add_f32_e32 v56, v59, v56
	v_add_f32_e32 v3, v0, v20
	ds_bpermute_b32 v57, v176, v56
	ds_bpermute_b32 v43, v176, v42
	ds_bpermute_b32 v27, v176, v26
	ds_bpermute_b32 v20, v176, v3
	v_lshl_add_u64 v[8:9], s[78:79], 0, v[78:79]
	v_lshl_add_u64 v[8:9], v[8:9], 0, s[18:19]
	v_lshl_add_u64 v[0:1], v[8:9], 0, s[0:1]
	s_waitcnt lgkmcnt(3)
	v_add_f32_e32 v44, v56, v57
	s_waitcnt lgkmcnt(2)
	v_add_f32_e32 v32, v42, v43
	s_waitcnt lgkmcnt(1)
	v_add_f32_e32 v16, v26, v27
	v_lshl_add_u64 v[8:9], v[0:1], 0, v[148:149]
	s_waitcnt lgkmcnt(0)
	v_add_f32_e32 v0, v3, v20
	ds_bpermute_b32 v45, v163, v44
	ds_bpermute_b32 v33, v163, v32
	ds_bpermute_b32 v17, v163, v16
	ds_bpermute_b32 v1, v163, v0
	v_cvt_pk_bf16_f32 v2, v4, v5
	v_cvt_pk_bf16_f32 v3, v6, v7
	v_cvt_pk_bf16_f32 v4, v10, v11
	v_cvt_pk_bf16_f32 v5, v18, v19
	global_store_dwordx4 v[40:41], v[52:55], off
	global_store_dwordx4 v[8:9], v[12:15], off
	global_store_dwordx4 v[8:9], v[2:5], off offset:256
	s_and_saveexec_b64 s[18:19], s[2:3]
	s_cbranch_execz .LBB0_1559
	s_waitcnt lgkmcnt(3)
	v_add_f32_e32 v3, v44, v45
	s_waitcnt lgkmcnt(0)
	v_add_f32_e32 v0, v0, v1
	v_add_f32_e32 v1, v16, v17
	v_add_f32_e32 v2, v32, v33
	global_atomic_add_f32 v[76:77], v3, off offset:512
	global_atomic_add_f32 v[76:77], v2, off offset:576
	global_atomic_add_f32 v[76:77], v1, off offset:640
	global_atomic_add_f32 v[76:77], v0, off offset:704

.LBB0_1719:
	s_mov_b32 s98, 0x40000
	s_mov_b32 s99, 0
	s_lshl_b32 s22, s53, 8
	s_lshl_b32 s20, s15, 8
	v_add_u32_e32 v140, s22, v225
	s_ashr_i32 s21, s20, 31
	s_lshl_b64 s[20:21], s[20:21], 1
	v_ashrrev_i32_e32 v141, 31, v140
	v_lshl_add_u64 v[142:143], v[204:205], 0, s[20:21]
	v_lshlrev_b64 v[128:129], 11, v[140:141]
	v_lshl_add_u64 v[130:131], v[142:143], 0, v[128:129]
	v_lshl_add_u64 v[190:191], v[130:131], 0, s[98:99]
	global_load_dwordx4 v[150:153], v[130:131], off
	global_load_dwordx4 v[154:157], v[130:131], off offset:256
	global_load_dwordx4 v[182:185], v[190:191], off
	global_load_dwordx4 v[186:189], v[190:191], off offset:256
	v_and_b32_e32 v131, 64, v230
	v_xor_b32_e32 v130, 16, v230
	v_add_u32_e32 v131, 64, v131
	v_cmp_lt_i32_e32 vcc, v130, v131
	v_xor_b32_e32 v132, 32, v230
	v_or_b32_e32 v134, 48, v140
	v_cndmask_b32_e32 v133, v230, v130, vcc
	v_or_b32_e32 v130, 16, v140
	v_cmp_lt_i32_e32 vcc, v132, v131
	v_ashrrev_i32_e32 v131, 31, v130
	v_lshlrev_b64 v[170:171], 11, v[130:131]
	v_lshl_add_u64 v[130:131], v[142:143], 0, v[170:171]
	v_lshl_add_u64 v[190:191], v[130:131], 0, s[98:99]
	global_load_dwordx4 v[158:161], v[130:131], off
	v_cndmask_b32_e32 v135, v230, v132, vcc
	v_or_b32_e32 v132, 32, v140
	v_lshlrev_b32_e32 v148, 2, v133
	v_ashrrev_i32_e32 v133, 31, v132
	v_lshlrev_b32_e32 v141, 2, v135
	v_ashrrev_i32_e32 v135, 31, v134
	v_lshlrev_b64 v[146:147], 11, v[132:133]
	v_lshlrev_b64 v[144:145], 11, v[134:135]
	v_lshl_add_u64 v[128:129], s[78:79], 0, v[128:129]
	v_lshl_add_u64 v[132:133], v[142:143], 0, v[146:147]
	v_lshl_add_u64 v[172:173], v[142:143], 0, v[144:145]
	v_lshl_add_u64 v[174:175], v[128:129], 0, s[20:21]
	global_load_dwordx4 v[162:165], v[130:131], off offset:256
	global_load_dwordx4 v[216:219], v[190:191], off
	global_load_dwordx4 v[220:223], v[190:191], off offset:256
	v_lshl_add_u64 v[190:191], v[132:133], 0, s[98:99]
	global_load_dwordx4 v[166:169], v[132:133], off
	global_load_dwordx4 v[136:139], v[132:133], off offset:256
	global_load_dwordx4 v[236:239], v[190:191], off
	global_load_dwordx4 v[240:243], v[190:191], off offset:256
	s_nop 0
	v_lshl_add_u64 v[190:191], v[172:173], 0, s[98:99]
	global_load_dwordx4 v[132:135], v[172:173], off
	global_load_dwordx4 v[128:131], v[172:173], off offset:256
	global_load_dwordx4 v[246:249], v[190:191], off
	global_load_dwordx4 v[250:253], v[190:191], off offset:256
	s_mov_b32 s15, s1
	v_lshl_add_u64 v[172:173], v[174:175], 0, s[14:15]
	v_lshl_add_u64 v[172:173], v[172:173], 0, v[200:201]
	s_ashr_i32 s23, s22, 31
	s_waitcnt vmcnt(14)
	v_lshlrev_b32_e32 v174, 16, v150
	v_and_b32_e32 v175, 0xffff0000, v150
	v_lshlrev_b32_e32 v150, 16, v151
	v_and_b32_e32 v151, 0xffff0000, v151
	v_lshlrev_b32_e32 v176, 16, v152
	v_and_b32_e32 v177, 0xffff0000, v152
	v_lshlrev_b32_e32 v152, 16, v153
	v_and_b32_e32 v153, 0xffff0000, v153
	v_lshlrev_b32_e32 v178, 16, v154
	v_and_b32_e32 v179, 0xffff0000, v154
	v_lshlrev_b32_e32 v154, 16, v155
	v_and_b32_e32 v155, 0xffff0000, v155
	v_lshlrev_b32_e32 v180, 16, v156
	v_and_b32_e32 v181, 0xffff0000, v156
	v_lshlrev_b32_e32 v156, 16, v157
	v_and_b32_e32 v157, 0xffff0000, v157
	v_pk_fma_f32 v[126:127], v[126:127], 0.5, v[150:151] op_sel_hi:[1,0,1]
	v_pk_fma_f32 v[124:125], v[124:125], 0.5, v[174:175] op_sel_hi:[1,0,1]
	v_pk_fma_f32 v[122:123], v[122:123], 0.5, v[152:153] op_sel_hi:[1,0,1]
	v_pk_fma_f32 v[120:121], v[120:121], 0.5, v[176:177] op_sel_hi:[1,0,1]
	v_pk_fma_f32 v[118:119], v[118:119], 0.5, v[154:155] op_sel_hi:[1,0,1]
	v_pk_fma_f32 v[150:151], v[116:117], 0.5, v[178:179] op_sel_hi:[1,0,1]
	v_pk_fma_f32 v[152:153], v[114:115], 0.5, v[156:157] op_sel_hi:[1,0,1]
	v_pk_fma_f32 v[154:155], v[112:113], 0.5, v[180:181] op_sel_hi:[1,0,1]
	v_cvt_pk_bf16_f32 v112, v124, v125
	v_mul_f32_e32 v117, v125, v125
	v_mul_f32_e32 v125, v127, v127
	v_cvt_pk_bf16_f32 v114, v120, v121
	v_cvt_pk_bf16_f32 v115, v122, v123
	v_mul_f32_e32 v121, v121, v121
	v_mul_f32_e32 v123, v123, v123
	v_cvt_pk_bf16_f32 v113, v126, v127
	v_mul_f32_e32 v127, v151, v151
	v_mul_f32_e32 v149, v119, v119
	v_fmac_f32_e32 v117, v124, v124
	v_fmac_f32_e32 v125, v126, v126
	v_fmac_f32_e32 v121, v120, v120
	v_fmac_f32_e32 v123, v122, v122
	global_store_dwordx4 v[172:173], v[112:115], off
	v_fmac_f32_e32 v127, v150, v150
	v_fmac_f32_e32 v149, v118, v118
	v_add_f32_e32 v112, v117, v125
	v_add_f32_e32 v113, v121, v123
	v_add_f32_e32 v114, v127, v149
	v_add_f32_e32 v112, v112, v113
	v_add_f32_e32 v112, v112, v114
	v_mul_f32_e32 v113, v155, v155
	v_mul_f32_e32 v114, v153, v153
	v_cvt_pk_bf16_f32 v116, v150, v151
	v_fmac_f32_e32 v113, v154, v154
	v_fmac_f32_e32 v114, v152, v152
	v_cvt_pk_bf16_f32 v117, v118, v119
	v_cvt_pk_bf16_f32 v118, v154, v155
	v_cvt_pk_bf16_f32 v119, v152, v153
	v_add_f32_e32 v113, v113, v114
	global_store_dwordx4 v[172:173], v[116:119], off offset:256
	s_waitcnt vmcnt(12)
	v_lshlrev_b32_e32 v114, 16, v158
	v_and_b32_e32 v115, 0xffff0000, v158
	v_lshlrev_b32_e32 v116, 16, v159
	v_and_b32_e32 v117, 0xffff0000, v159
	v_pk_fma_f32 v[110:111], v[110:111], 0.5, v[116:117] op_sel_hi:[1,0,1]
	v_pk_fma_f32 v[114:115], v[108:109], 0.5, v[114:115] op_sel_hi:[1,0,1]
	v_cvt_pk_bf16_f32 v109, v110, v111
	v_cvt_pk_bf16_f32 v108, v114, v115
	v_mul_f32_e32 v115, v115, v115
	v_mul_f32_e32 v111, v111, v111
	v_fmac_f32_e32 v115, v114, v114
	v_fmac_f32_e32 v111, v110, v110
	v_add_f32_e32 v116, v115, v111
	v_lshlrev_b32_e32 v110, 16, v160
	v_and_b32_e32 v111, 0xffff0000, v160
	v_lshlrev_b32_e32 v114, 16, v161
	v_and_b32_e32 v115, 0xffff0000, v161
	v_pk_fma_f32 v[104:105], v[104:105], 0.5, v[110:111] op_sel_hi:[1,0,1]
	v_pk_fma_f32 v[106:107], v[106:107], 0.5, v[114:115] op_sel_hi:[1,0,1]
	v_cvt_pk_bf16_f32 v110, v104, v105
	v_mul_f32_e32 v105, v105, v105
	v_fmac_f32_e32 v105, v104, v104
	v_mul_f32_e32 v104, v107, v107
	v_fmac_f32_e32 v104, v106, v106
	v_add_f32_e32 v104, v105, v104
	v_add_f32_e32 v114, v116, v104
	v_lshl_add_u64 v[104:105], s[78:79], 0, v[170:171]
	v_lshl_add_u64 v[104:105], v[104:105], 0, s[20:21]
	v_lshl_add_u64 v[104:105], v[104:105], 0, s[14:15]
	v_cvt_pk_bf16_f32 v111, v106, v107
	v_lshl_add_u64 v[104:105], v[104:105], 0, v[200:201]
	v_lshlrev_b32_e32 v106, 16, v162
	v_and_b32_e32 v107, 0xffff0000, v162
	global_store_dwordx4 v[104:105], v[108:111], off
	v_pk_fma_f32 v[106:107], v[100:101], 0.5, v[106:107] op_sel_hi:[1,0,1]
	v_add_f32_e32 v112, v113, v112
	v_lshlrev_b32_e32 v108, 16, v163
	v_and_b32_e32 v109, 0xffff0000, v163
	v_pk_fma_f32 v[102:103], v[102:103], 0.5, v[108:109] op_sel_hi:[1,0,1]
	v_mul_f32_e32 v101, v107, v107
	v_cvt_pk_bf16_f32 v100, v106, v107
	v_fmac_f32_e32 v101, v106, v106
	v_mul_f32_e32 v106, v103, v103
	v_fmac_f32_e32 v106, v102, v102
	v_add_f32_e32 v101, v101, v106
	v_lshlrev_b32_e32 v106, 16, v164
	v_and_b32_e32 v107, 0xffff0000, v164
	v_lshlrev_b32_e32 v108, 16, v165
	v_and_b32_e32 v109, 0xffff0000, v165
	v_pk_fma_f32 v[98:99], v[98:99], 0.5, v[108:109] op_sel_hi:[1,0,1]
	v_pk_fma_f32 v[96:97], v[96:97], 0.5, v[106:107] op_sel_hi:[1,0,1]
	v_mul_f32_e32 v107, v99, v99
	v_mul_f32_e32 v106, v97, v97
	v_fmac_f32_e32 v106, v96, v96
	v_fmac_f32_e32 v107, v98, v98
	v_add_f32_e32 v101, v114, v101
	v_add_f32_e32 v106, v106, v107
	v_add_f32_e32 v106, v106, v101
	v_cvt_pk_bf16_f32 v101, v102, v103
	v_cvt_pk_bf16_f32 v102, v96, v97
	v_cvt_pk_bf16_f32 v103, v98, v99
	global_store_dwordx4 v[104:105], v[100:103], off offset:256
	s_waitcnt vmcnt(10)
	v_lshlrev_b32_e32 v98, 16, v166
	v_and_b32_e32 v99, 0xffff0000, v166
	v_lshlrev_b32_e32 v100, 16, v167
	v_and_b32_e32 v101, 0xffff0000, v167
	v_pk_fma_f32 v[94:95], v[94:95], 0.5, v[100:101] op_sel_hi:[1,0,1]
	v_pk_fma_f32 v[98:99], v[92:93], 0.5, v[98:99] op_sel_hi:[1,0,1]
	v_cvt_pk_bf16_f32 v93, v94, v95
	v_cvt_pk_bf16_f32 v92, v98, v99
	v_mul_f32_e32 v99, v99, v99
	v_mul_f32_e32 v95, v95, v95
	v_fmac_f32_e32 v99, v98, v98
	v_fmac_f32_e32 v95, v94, v94
	v_add_f32_e32 v100, v99, v95
	v_lshlrev_b32_e32 v94, 16, v168
	v_and_b32_e32 v95, 0xffff0000, v168
	v_lshlrev_b32_e32 v98, 16, v169
	v_and_b32_e32 v99, 0xffff0000, v169
	v_pk_fma_f32 v[88:89], v[88:89], 0.5, v[94:95] op_sel_hi:[1,0,1]
	v_pk_fma_f32 v[90:91], v[90:91], 0.5, v[98:99] op_sel_hi:[1,0,1]
	v_cvt_pk_bf16_f32 v94, v88, v89
	v_mul_f32_e32 v89, v89, v89
	v_fmac_f32_e32 v89, v88, v88
	v_mul_f32_e32 v88, v91, v91
	v_fmac_f32_e32 v88, v90, v90
	v_add_f32_e32 v88, v89, v88
	v_add_f32_e32 v98, v100, v88
	v_lshl_add_u64 v[88:89], s[78:79], 0, v[146:147]
	v_lshl_add_u64 v[88:89], v[88:89], 0, s[20:21]
	v_lshl_add_u64 v[88:89], v[88:89], 0, s[14:15]
	v_cvt_pk_bf16_f32 v95, v90, v91
	v_lshl_add_u64 v[88:89], v[88:89], 0, v[200:201]
	v_lshlrev_b32_e32 v90, 16, v136
	v_and_b32_e32 v91, 0xffff0000, v136
	global_store_dwordx4 v[88:89], v[92:95], off
	v_pk_fma_f32 v[90:91], v[84:85], 0.5, v[90:91] op_sel_hi:[1,0,1]
	ds_bpermute_b32 v113, v148, v112
	v_lshlrev_b32_e32 v92, 16, v137
	v_and_b32_e32 v93, 0xffff0000, v137
	v_pk_fma_f32 v[86:87], v[86:87], 0.5, v[92:93] op_sel_hi:[1,0,1]
	v_mul_f32_e32 v85, v91, v91
	v_cvt_pk_bf16_f32 v84, v90, v91
	v_fmac_f32_e32 v85, v90, v90
	v_mul_f32_e32 v90, v87, v87
	v_fmac_f32_e32 v90, v86, v86
	v_add_f32_e32 v85, v85, v90
	v_lshlrev_b32_e32 v90, 16, v138
	v_and_b32_e32 v91, 0xffff0000, v138
	v_lshlrev_b32_e32 v92, 16, v139
	v_and_b32_e32 v93, 0xffff0000, v139
	v_pk_fma_f32 v[82:83], v[82:83], 0.5, v[92:93] op_sel_hi:[1,0,1]
	v_pk_fma_f32 v[80:81], v[80:81], 0.5, v[90:91] op_sel_hi:[1,0,1]
	v_mul_f32_e32 v91, v83, v83
	v_mul_f32_e32 v90, v81, v81
	v_fmac_f32_e32 v90, v80, v80
	v_fmac_f32_e32 v91, v82, v82
	v_add_f32_e32 v85, v98, v85
	v_add_f32_e32 v90, v90, v91
	v_add_f32_e32 v90, v90, v85
	v_cvt_pk_bf16_f32 v85, v86, v87
	v_cvt_pk_bf16_f32 v86, v80, v81
	v_cvt_pk_bf16_f32 v87, v82, v83
	global_store_dwordx4 v[88:89], v[84:87], off offset:256
	s_waitcnt vmcnt(8)
	v_lshlrev_b32_e32 v82, 16, v132
	v_and_b32_e32 v83, 0xffff0000, v132
	v_lshlrev_b32_e32 v84, 16, v133
	v_and_b32_e32 v85, 0xffff0000, v133
	v_pk_fma_f32 v[78:79], v[78:79], 0.5, v[84:85] op_sel_hi:[1,0,1]
	v_pk_fma_f32 v[82:83], v[76:77], 0.5, v[82:83] op_sel_hi:[1,0,1]
	v_cvt_pk_bf16_f32 v77, v78, v79
	v_cvt_pk_bf16_f32 v76, v82, v83
	v_mul_f32_e32 v83, v83, v83
	v_mul_f32_e32 v79, v79, v79
	v_fmac_f32_e32 v83, v82, v82
	v_fmac_f32_e32 v79, v78, v78
	v_add_f32_e32 v84, v83, v79
	v_lshlrev_b32_e32 v78, 16, v134
	v_and_b32_e32 v79, 0xffff0000, v134
	v_lshlrev_b32_e32 v82, 16, v135
	v_and_b32_e32 v83, 0xffff0000, v135
	v_pk_fma_f32 v[72:73], v[72:73], 0.5, v[78:79] op_sel_hi:[1,0,1]
	v_pk_fma_f32 v[74:75], v[74:75], 0.5, v[82:83] op_sel_hi:[1,0,1]
	v_cvt_pk_bf16_f32 v78, v72, v73
	v_mul_f32_e32 v73, v73, v73
	v_fmac_f32_e32 v73, v72, v72
	v_mul_f32_e32 v72, v75, v75
	v_cvt_pk_bf16_f32 v79, v74, v75
	v_fmac_f32_e32 v72, v74, v74
	v_lshlrev_b32_e32 v74, 16, v128
	v_and_b32_e32 v75, 0xffff0000, v128
	v_lshlrev_b32_e32 v82, 16, v129
	v_and_b32_e32 v83, 0xffff0000, v129
	v_pk_fma_f32 v[70:71], v[70:71], 0.5, v[82:83] op_sel_hi:[1,0,1]
	v_pk_fma_f32 v[68:69], v[68:69], 0.5, v[74:75] op_sel_hi:[1,0,1]
	v_mul_f32_e32 v75, v71, v71
	v_mul_f32_e32 v74, v69, v69
	v_add_f32_e32 v72, v73, v72
	v_fmac_f32_e32 v74, v68, v68
	v_fmac_f32_e32 v75, v70, v70
	v_add_f32_e32 v84, v84, v72
	v_add_f32_e32 v74, v74, v75
	v_add_f32_e32 v84, v84, v74
	v_lshlrev_b32_e32 v74, 16, v130
	v_and_b32_e32 v75, 0xffff0000, v130
	v_lshlrev_b32_e32 v82, 16, v131
	v_and_b32_e32 v83, 0xffff0000, v131
	v_pk_fma_f32 v[82:83], v[66:67], 0.5, v[82:83] op_sel_hi:[1,0,1]
	v_pk_fma_f32 v[74:75], v[64:65], 0.5, v[74:75] op_sel_hi:[1,0,1]
	v_mul_f32_e32 v65, v83, v83
	v_mul_f32_e32 v64, v75, v75
	v_fmac_f32_e32 v64, v74, v74
	v_fmac_f32_e32 v65, v82, v82
	v_add_f32_e32 v64, v64, v65
	v_add_f32_e32 v64, v64, v84
	ds_bpermute_b32 v107, v148, v106
	ds_bpermute_b32 v91, v148, v90
	ds_bpermute_b32 v65, v148, v64
	s_waitcnt lgkmcnt(3)
	v_add_f32_e32 v112, v112, v113
	ds_bpermute_b32 v113, v141, v112
	s_waitcnt lgkmcnt(3)
	v_add_f32_e32 v96, v106, v107
	s_waitcnt lgkmcnt(2)
	v_add_f32_e32 v80, v90, v91
	s_waitcnt lgkmcnt(1)
	v_add_f32_e32 v64, v64, v65
	ds_bpermute_b32 v97, v141, v96
	ds_bpermute_b32 v81, v141, v80
	v_lshl_add_u64 v[72:73], s[78:79], 0, v[144:145]
	ds_bpermute_b32 v65, v141, v64
	v_lshl_add_u64 v[72:73], v[72:73], 0, s[20:21]
	v_lshl_add_u64 v[72:73], v[72:73], 0, s[14:15]
	v_lshl_add_u64 v[72:73], v[72:73], 0, v[200:201]
	global_store_dwordx4 v[72:73], v[76:79], off
	v_cvt_pk_bf16_f32 v66, v68, v69
	v_cvt_pk_bf16_f32 v67, v70, v71
	v_cvt_pk_bf16_f32 v68, v74, v75
	v_cvt_pk_bf16_f32 v69, v82, v83
	v_lshl_add_u64 v[76:77], s[22:23], 2, v[206:207]
	global_store_dwordx4 v[72:73], v[66:69], off offset:256
	s_and_saveexec_b64 s[22:23], s[2:3]
	s_cbranch_execz .LBB0_1721
	s_waitcnt lgkmcnt(3)
	v_add_f32_e32 v67, v112, v113
	s_waitcnt lgkmcnt(0)
	v_add_f32_e32 v64, v64, v65
	v_add_f32_e32 v65, v80, v81
	v_add_f32_e32 v66, v96, v97
	global_atomic_add_f32 v[76:77], v67, off
	global_atomic_add_f32 v[76:77], v66, off offset:64
	global_atomic_add_f32 v[76:77], v65, off offset:128
	global_atomic_add_f32 v[76:77], v64, off offset:192
.LBB0_1721:
	s_or_b64 exec, exec, s[22:23]
	s_waitcnt vmcnt(8)
	v_add_u32_e32 v64, 0x80, v140
	s_waitcnt lgkmcnt(0)
	v_ashrrev_i32_e32 v65, 31, v64
	v_lshlrev_b64 v[64:65], 11, v[64:65]
	v_lshl_add_u64 v[66:67], v[142:143], 0, v[64:65]
	v_mov_b32_e32 v82, v182
	v_mov_b32_e32 v83, v183
	v_mov_b32_e32 v84, v184
	v_mov_b32_e32 v85, v185
	v_mov_b32_e32 v86, v186
	v_mov_b32_e32 v87, v187
	v_mov_b32_e32 v88, v188
	v_mov_b32_e32 v89, v189
	v_add_u32_e32 v66, 0x90, v140
	v_ashrrev_i32_e32 v67, 31, v66
	v_lshlrev_b64 v[102:103], 11, v[66:67]
	v_lshl_add_u64 v[66:67], v[142:143], 0, v[102:103]
	v_mov_b32_e32 v90, v216
	v_mov_b32_e32 v91, v217
	v_mov_b32_e32 v92, v218
	v_mov_b32_e32 v93, v219
	v_add_u32_e32 v68, 0xa0, v140
	v_add_u32_e32 v70, 0xb0, v140
	v_ashrrev_i32_e32 v69, 31, v68
	v_ashrrev_i32_e32 v71, 31, v70
	v_lshlrev_b64 v[80:81], 11, v[68:69]
	v_lshlrev_b64 v[78:79], 11, v[70:71]
	v_lshl_add_u64 v[68:69], v[142:143], 0, v[80:81]
	v_lshl_add_u64 v[104:105], v[142:143], 0, v[78:79]
	v_lshl_add_u64 v[106:107], s[78:79], 0, v[64:65]
	v_mov_b32_e32 v94, v220
	v_mov_b32_e32 v95, v221
	v_mov_b32_e32 v96, v222
	v_mov_b32_e32 v97, v223
	v_mov_b32_e32 v98, v236
	v_mov_b32_e32 v99, v237
	v_mov_b32_e32 v100, v238
	v_mov_b32_e32 v101, v239
	v_mov_b32_e32 v72, v240
	v_mov_b32_e32 v73, v241
	v_mov_b32_e32 v74, v242
	v_mov_b32_e32 v75, v243
	s_nop 0
	v_mov_b32_e32 v68, v246
	v_mov_b32_e32 v69, v247
	v_mov_b32_e32 v70, v248
	v_mov_b32_e32 v71, v249
	v_mov_b32_e32 v64, v250
	v_mov_b32_e32 v65, v251
	v_mov_b32_e32 v66, v252
	v_mov_b32_e32 v67, v253
	v_lshl_add_u64 v[104:105], v[106:107], 0, s[20:21]
	v_lshl_add_u64 v[104:105], v[104:105], 0, s[14:15]
	v_lshl_add_u64 v[104:105], v[104:105], 0, v[200:201]
	v_lshlrev_b32_e32 v106, 16, v82
	v_and_b32_e32 v107, 0xffff0000, v82
	v_lshlrev_b32_e32 v82, 16, v83
	v_and_b32_e32 v83, 0xffff0000, v83
	v_lshlrev_b32_e32 v108, 16, v84
	v_and_b32_e32 v109, 0xffff0000, v84
	v_lshlrev_b32_e32 v84, 16, v85
	v_and_b32_e32 v85, 0xffff0000, v85
	v_lshlrev_b32_e32 v110, 16, v86
	v_and_b32_e32 v111, 0xffff0000, v86
	v_lshlrev_b32_e32 v86, 16, v87
	v_and_b32_e32 v87, 0xffff0000, v87
	v_lshlrev_b32_e32 v112, 16, v88
	v_and_b32_e32 v113, 0xffff0000, v88
	v_lshlrev_b32_e32 v88, 16, v89
	v_and_b32_e32 v89, 0xffff0000, v89
	v_pk_fma_f32 v[62:63], v[62:63], 0.5, v[82:83] op_sel_hi:[1,0,1]
	v_pk_fma_f32 v[60:61], v[60:61], 0.5, v[106:107] op_sel_hi:[1,0,1]
	v_pk_fma_f32 v[58:59], v[58:59], 0.5, v[84:85] op_sel_hi:[1,0,1]
	v_pk_fma_f32 v[56:57], v[56:57], 0.5, v[108:109] op_sel_hi:[1,0,1]
	v_lshlrev_b32_e32 v114, 16, v90
	v_and_b32_e32 v115, 0xffff0000, v90
	v_lshlrev_b32_e32 v90, 16, v91
	v_and_b32_e32 v91, 0xffff0000, v91
	v_pk_fma_f32 v[82:83], v[50:51], 0.5, v[86:87] op_sel_hi:[1,0,1]
	v_pk_fma_f32 v[84:85], v[48:49], 0.5, v[110:111] op_sel_hi:[1,0,1]
	v_pk_fma_f32 v[86:87], v[46:47], 0.5, v[88:89] op_sel_hi:[1,0,1]
	v_pk_fma_f32 v[88:89], v[44:45], 0.5, v[112:113] op_sel_hi:[1,0,1]
	v_cvt_pk_bf16_f32 v44, v60, v61
	v_cvt_pk_bf16_f32 v45, v62, v63
	v_cvt_pk_bf16_f32 v46, v56, v57
	v_cvt_pk_bf16_f32 v47, v58, v59
	v_pk_fma_f32 v[54:55], v[54:55], 0.5, v[90:91] op_sel_hi:[1,0,1]
	v_cvt_pk_bf16_f32 v48, v84, v85
	v_cvt_pk_bf16_f32 v49, v82, v83
	v_cvt_pk_bf16_f32 v50, v88, v89
	v_cvt_pk_bf16_f32 v51, v86, v87
	global_store_dwordx4 v[104:105], v[44:47], off
	global_store_dwordx4 v[104:105], v[48:51], off offset:256
	v_pk_fma_f32 v[90:91], v[52:53], 0.5, v[114:115] op_sel_hi:[1,0,1]
	v_lshlrev_b32_e32 v46, 16, v92
	v_and_b32_e32 v47, 0xffff0000, v92
	v_cvt_pk_bf16_f32 v53, v54, v55
	v_mul_f32_e32 v55, v55, v55
	v_lshlrev_b32_e32 v48, 16, v93
	v_and_b32_e32 v49, 0xffff0000, v93
	v_pk_fma_f32 v[40:41], v[40:41], 0.5, v[46:47] op_sel_hi:[1,0,1]
	v_cvt_pk_bf16_f32 v52, v90, v91
	v_mul_f32_e32 v91, v91, v91
	v_fmac_f32_e32 v55, v54, v54
	v_pk_fma_f32 v[42:43], v[42:43], 0.5, v[48:49] op_sel_hi:[1,0,1]
	v_cvt_pk_bf16_f32 v54, v40, v41
	v_mul_f32_e32 v41, v41, v41
	v_fmac_f32_e32 v91, v90, v90
	v_fmac_f32_e32 v41, v40, v40
	v_mul_f32_e32 v40, v43, v43
	v_add_f32_e32 v50, v91, v55
	v_cvt_pk_bf16_f32 v55, v42, v43
	v_fmac_f32_e32 v40, v42, v42
	v_lshlrev_b32_e32 v42, 16, v94
	v_and_b32_e32 v43, 0xffff0000, v94
	v_lshlrev_b32_e32 v46, 16, v95
	v_and_b32_e32 v47, 0xffff0000, v95
	v_pk_fma_f32 v[42:43], v[36:37], 0.5, v[42:43] op_sel_hi:[1,0,1]
	v_pk_fma_f32 v[38:39], v[38:39], 0.5, v[46:47] op_sel_hi:[1,0,1]
	v_mul_f32_e32 v37, v43, v43
	v_cvt_pk_bf16_f32 v36, v42, v43
	v_fmac_f32_e32 v37, v42, v42
	v_mul_f32_e32 v42, v39, v39
	v_fmac_f32_e32 v42, v38, v38
	v_add_f32_e32 v37, v37, v42
	v_lshlrev_b32_e32 v42, 16, v96
	v_and_b32_e32 v43, 0xffff0000, v96
	v_lshlrev_b32_e32 v46, 16, v97
	v_and_b32_e32 v47, 0xffff0000, v97
	v_add_f32_e32 v40, v41, v40
	v_pk_fma_f32 v[34:35], v[34:35], 0.5, v[46:47] op_sel_hi:[1,0,1]
	v_pk_fma_f32 v[32:33], v[32:33], 0.5, v[42:43] op_sel_hi:[1,0,1]
	v_add_f32_e32 v48, v50, v40
	v_lshl_add_u64 v[40:41], s[78:79], 0, v[102:103]
	v_mul_f32_e32 v42, v33, v33
	v_mul_f32_e32 v43, v35, v35
	v_lshl_add_u64 v[40:41], v[40:41], 0, s[20:21]
	v_fmac_f32_e32 v42, v32, v32
	v_fmac_f32_e32 v43, v34, v34
	v_lshl_add_u64 v[40:41], v[40:41], 0, s[14:15]
	v_add_f32_e32 v37, v48, v37
	v_add_f32_e32 v42, v42, v43
	v_lshl_add_u64 v[40:41], v[40:41], 0, v[200:201]
	v_add_f32_e32 v42, v42, v37
	v_cvt_pk_bf16_f32 v37, v38, v39
	v_cvt_pk_bf16_f32 v38, v32, v33
	v_cvt_pk_bf16_f32 v39, v34, v35
	global_store_dwordx4 v[40:41], v[36:39], off offset:256
	v_lshlrev_b32_e32 v34, 16, v98
	v_and_b32_e32 v35, 0xffff0000, v98
	v_lshlrev_b32_e32 v36, 16, v99
	v_and_b32_e32 v37, 0xffff0000, v99
	v_pk_fma_f32 v[30:31], v[30:31], 0.5, v[36:37] op_sel_hi:[1,0,1]
	v_pk_fma_f32 v[34:35], v[28:29], 0.5, v[34:35] op_sel_hi:[1,0,1]
	v_cvt_pk_bf16_f32 v29, v30, v31
	v_cvt_pk_bf16_f32 v28, v34, v35
	v_mul_f32_e32 v35, v35, v35
	v_mul_f32_e32 v31, v31, v31
	v_fmac_f32_e32 v35, v34, v34
	v_fmac_f32_e32 v31, v30, v30
	v_add_f32_e32 v36, v35, v31
	v_lshlrev_b32_e32 v30, 16, v100
	v_and_b32_e32 v31, 0xffff0000, v100
	v_lshlrev_b32_e32 v34, 16, v101
	v_and_b32_e32 v35, 0xffff0000, v101
	v_pk_fma_f32 v[24:25], v[24:25], 0.5, v[30:31] op_sel_hi:[1,0,1]
	v_pk_fma_f32 v[26:27], v[26:27], 0.5, v[34:35] op_sel_hi:[1,0,1]
	v_cvt_pk_bf16_f32 v30, v24, v25
	v_mul_f32_e32 v25, v25, v25
	v_fmac_f32_e32 v25, v24, v24
	v_mul_f32_e32 v24, v27, v27
	v_fmac_f32_e32 v24, v26, v26
	v_add_f32_e32 v24, v25, v24
	v_add_f32_e32 v34, v36, v24
	v_lshl_add_u64 v[24:25], s[78:79], 0, v[80:81]
	v_lshl_add_u64 v[24:25], v[24:25], 0, s[20:21]
	v_lshl_add_u64 v[24:25], v[24:25], 0, s[14:15]
	v_cvt_pk_bf16_f32 v31, v26, v27
	v_lshl_add_u64 v[24:25], v[24:25], 0, v[200:201]
	v_lshlrev_b32_e32 v26, 16, v72
	v_and_b32_e32 v27, 0xffff0000, v72
	global_store_dwordx4 v[24:25], v[28:31], off
	v_pk_fma_f32 v[26:27], v[20:21], 0.5, v[26:27] op_sel_hi:[1,0,1]
	v_mul_f32_e32 v61, v61, v61
	v_lshlrev_b32_e32 v28, 16, v73
	v_and_b32_e32 v29, 0xffff0000, v73
	v_pk_fma_f32 v[22:23], v[22:23], 0.5, v[28:29] op_sel_hi:[1,0,1]
	v_mul_f32_e32 v21, v27, v27
	v_cvt_pk_bf16_f32 v20, v26, v27
	v_fmac_f32_e32 v21, v26, v26
	v_mul_f32_e32 v26, v23, v23
	v_fmac_f32_e32 v26, v22, v22
	v_add_f32_e32 v21, v21, v26
	v_lshlrev_b32_e32 v26, 16, v74
	v_and_b32_e32 v27, 0xffff0000, v74
	v_lshlrev_b32_e32 v28, 16, v75
	v_and_b32_e32 v29, 0xffff0000, v75
	v_pk_fma_f32 v[18:19], v[18:19], 0.5, v[28:29] op_sel_hi:[1,0,1]
	v_pk_fma_f32 v[16:17], v[16:17], 0.5, v[26:27] op_sel_hi:[1,0,1]
	v_mul_f32_e32 v27, v19, v19
	v_mul_f32_e32 v26, v17, v17
	v_fmac_f32_e32 v26, v16, v16
	v_fmac_f32_e32 v27, v18, v18
	v_add_f32_e32 v21, v34, v21
	v_add_f32_e32 v26, v26, v27
	v_add_f32_e32 v26, v26, v21
	v_cvt_pk_bf16_f32 v21, v22, v23
	v_cvt_pk_bf16_f32 v22, v16, v17
	v_cvt_pk_bf16_f32 v23, v18, v19
	global_store_dwordx4 v[24:25], v[20:23], off offset:256
	v_lshlrev_b32_e32 v18, 16, v68
	v_and_b32_e32 v19, 0xffff0000, v68
	v_lshlrev_b32_e32 v20, 16, v69
	v_and_b32_e32 v21, 0xffff0000, v69
	v_pk_fma_f32 v[14:15], v[14:15], 0.5, v[20:21] op_sel_hi:[1,0,1]
	v_pk_fma_f32 v[18:19], v[12:13], 0.5, v[18:19] op_sel_hi:[1,0,1]
	v_cvt_pk_bf16_f32 v13, v14, v15
	v_cvt_pk_bf16_f32 v12, v18, v19
	v_mul_f32_e32 v19, v19, v19
	v_mul_f32_e32 v15, v15, v15
	v_fmac_f32_e32 v19, v18, v18
	v_fmac_f32_e32 v15, v14, v14
	v_add_f32_e32 v20, v19, v15
	v_lshlrev_b32_e32 v14, 16, v70
	v_and_b32_e32 v15, 0xffff0000, v70
	v_lshlrev_b32_e32 v18, 16, v71
	v_and_b32_e32 v19, 0xffff0000, v71
	v_pk_fma_f32 v[8:9], v[8:9], 0.5, v[14:15] op_sel_hi:[1,0,1]
	v_pk_fma_f32 v[10:11], v[10:11], 0.5, v[18:19] op_sel_hi:[1,0,1]
	v_cvt_pk_bf16_f32 v14, v8, v9
	v_mul_f32_e32 v9, v9, v9
	v_fmac_f32_e32 v9, v8, v8
	v_mul_f32_e32 v8, v11, v11
	v_cvt_pk_bf16_f32 v15, v10, v11
	v_fmac_f32_e32 v8, v10, v10
	v_lshlrev_b32_e32 v10, 16, v64
	v_and_b32_e32 v11, 0xffff0000, v64
	v_lshlrev_b32_e32 v18, 16, v65
	v_and_b32_e32 v19, 0xffff0000, v65
	v_pk_fma_f32 v[6:7], v[6:7], 0.5, v[18:19] op_sel_hi:[1,0,1]
	v_pk_fma_f32 v[4:5], v[4:5], 0.5, v[10:11] op_sel_hi:[1,0,1]
	v_mul_f32_e32 v11, v7, v7
	v_mul_f32_e32 v10, v5, v5
	v_add_f32_e32 v8, v9, v8
	v_fmac_f32_e32 v10, v4, v4
	v_fmac_f32_e32 v11, v6, v6
	v_add_f32_e32 v20, v20, v8
	v_add_f32_e32 v10, v10, v11
	v_mul_f32_e32 v63, v63, v63
	v_mul_f32_e32 v57, v57, v57
	v_mul_f32_e32 v59, v59, v59
	v_add_f32_e32 v20, v20, v10
	v_lshlrev_b32_e32 v10, 16, v66
	v_and_b32_e32 v11, 0xffff0000, v66
	v_lshlrev_b32_e32 v18, 16, v67
	v_and_b32_e32 v19, 0xffff0000, v67
	v_mul_f32_e32 v85, v85, v85
	v_mul_f32_e32 v83, v83, v83
	v_fmac_f32_e32 v61, v60, v60
	v_fmac_f32_e32 v63, v62, v62
	v_fmac_f32_e32 v57, v56, v56
	v_fmac_f32_e32 v59, v58, v58
	v_pk_fma_f32 v[18:19], v[2:3], 0.5, v[18:19] op_sel_hi:[1,0,1]
	v_pk_fma_f32 v[10:11], v[0:1], 0.5, v[10:11] op_sel_hi:[1,0,1]
	v_mul_f32_e32 v89, v89, v89
	v_mul_f32_e32 v87, v87, v87
	v_fmac_f32_e32 v85, v84, v84
	v_fmac_f32_e32 v83, v82, v82
	v_add_f32_e32 v56, v61, v63
	v_add_f32_e32 v57, v57, v59
	v_mul_f32_e32 v0, v11, v11
	v_mul_f32_e32 v1, v19, v19
	v_fmac_f32_e32 v89, v88, v88
	v_fmac_f32_e32 v87, v86, v86
	v_add_f32_e32 v58, v85, v83
	v_add_f32_e32 v56, v56, v57
	v_fmac_f32_e32 v0, v10, v10
	v_fmac_f32_e32 v1, v18, v18
	v_add_f32_e32 v59, v89, v87
	v_add_f32_e32 v56, v56, v58
	v_add_f32_e32 v0, v0, v1
	v_add_f32_e32 v56, v59, v56
	v_add_f32_e32 v3, v0, v20
	ds_bpermute_b32 v57, v148, v56
	ds_bpermute_b32 v43, v148, v42
	ds_bpermute_b32 v27, v148, v26
	ds_bpermute_b32 v20, v148, v3
	v_lshl_add_u64 v[8:9], s[78:79], 0, v[78:79]
	v_lshl_add_u64 v[8:9], v[8:9], 0, s[20:21]
	v_lshl_add_u64 v[0:1], v[8:9], 0, s[14:15]
	s_waitcnt lgkmcnt(3)
	v_add_f32_e32 v44, v56, v57
	s_waitcnt lgkmcnt(2)
	v_add_f32_e32 v32, v42, v43
	s_waitcnt lgkmcnt(1)
	v_add_f32_e32 v16, v26, v27
	v_lshl_add_u64 v[8:9], v[0:1], 0, v[200:201]
	s_waitcnt lgkmcnt(0)
	v_add_f32_e32 v0, v3, v20
	ds_bpermute_b32 v45, v141, v44
	ds_bpermute_b32 v33, v141, v32
	ds_bpermute_b32 v17, v141, v16
	ds_bpermute_b32 v1, v141, v0
	v_cvt_pk_bf16_f32 v2, v4, v5
	v_cvt_pk_bf16_f32 v3, v6, v7
	v_cvt_pk_bf16_f32 v4, v10, v11
	v_cvt_pk_bf16_f32 v5, v18, v19
	global_store_dwordx4 v[40:41], v[52:55], off
	global_store_dwordx4 v[8:9], v[12:15], off
	global_store_dwordx4 v[8:9], v[2:5], off offset:256
	s_and_saveexec_b64 s[20:21], s[2:3]
	s_cbranch_execz .LBB0_1723
	s_waitcnt lgkmcnt(3)
	v_add_f32_e32 v3, v44, v45
	s_waitcnt lgkmcnt(0)
	v_add_f32_e32 v0, v0, v1
	v_add_f32_e32 v1, v16, v17
	v_add_f32_e32 v2, v32, v33
	global_atomic_add_f32 v[76:77], v3, off offset:512
	global_atomic_add_f32 v[76:77], v2, off offset:576
	global_atomic_add_f32 v[76:77], v1, off offset:640
	global_atomic_add_f32 v[76:77], v0, off offset:704
